# scan step: counted lgkmcnt waits per operand group and next-step LDS reads issued earlier (same instruction mix otherwise), X=10
# baseline (speedup 1.0000x reference)
; #define LAS __attribute__((address_space(3)))
; template <int CTRL> __device__ __forceinline__ float dppf(float x) { return __builtin_bit_cast(float, __builtin_amdgcn_mov_dpp(__builtin_bit_cast(int, x), CTRL, 0xf, 0xf, true)); }
; __device__ __forceinline__ void rwkv_item(LAS unsigned char* lds, int l, const bf16_t* PROJ, const bf16_t* LO, bf16_t* YR, float* BON, int b, int h, int qv) {
;     ...
;         for (int ci = 0; ci < NCH; ++ci) {
;             const LAS float* pk = base + (ci & 1) * BUFF + 4 * kq; const LAS float* pv = base + (ci & 1) * BUFF + 10240 + rl; const LAS float* ps = base + (ci & 1) * BUFF + 11264;
;             LAS float* py = yA + (ci & 1) * 4096 + rl * 4 + (kq >> 2);
;             f32x4 kk4 = *(const LAS f32x4*)(pk), wr4 = *(const LAS f32x4*)(pk + 2048), w4 = *(const LAS f32x4*)(pk + 4096), k4 = *(const LAS f32x4*)(pk + 6144), a4 = *(const LAS f32x4*)(pk + 8192);
;             float vv[2] = {pv[0], pv[4]}; f32x2 sc = *(const LAS f32x2*)(ps);
; #pragma unroll 32
;             for (int t = 0; t < CH; ++t) {
;                 const int tn = (t + 1) & (CH - 1);
;                 const LAS float* pn = pk + tn * 64;
;                 const f32x4 nkk = *(const LAS f32x4*)(pn), nwr = *(const LAS f32x4*)(pn + 2048), nw = *(const LAS f32x4*)(pn + 4096), nk = *(const LAS f32x4*)(pn + 6144), na = *(const LAS f32x4*)(pn + 8192);
;                 const float nv0 = pv[tn * 32], nv1 = pv[tn * 32 + 4]; const f32x2 nsc = *(const LAS f32x2*)(ps + 2 * tn);
;                 float sa[2], yp[2];
; #pragma unroll
;                 for (int c = 0; c < 2; ++c) { const f32x2 pa = S23[c] * kk4.hi + S01[c] * kk4.lo, pb = S23[c] * wr4.hi + S01[c] * wr4.lo; sa[c] = pa.x + pa.y; yp[c] = pb.x + pb.y; }
; #pragma unroll
;                 for (int c = 0; c < 2; ++c) { sa[c] = sum16(sa[c]); yp[c] += dppf<0xB1>(yp[c]); yp[c] += dppf<0x4E>(yp[c]); }
; #pragma unroll
;                 for (int c = 0; c < 2; ++c) {
;                     S01[c] = S01[c] * w4.lo + (k4.lo * vv[c] - a4.lo * sa[c]);
;                     S23[c] = S23[c] * w4.hi + (k4.hi * vv[c] - a4.hi * sa[c]);
;                     py[(t * 32 + 4 * c) * 4] = yp[c] + 0.25f * (vv[c] * sc.x - sa[c] * sc.y);
;                 }
;                 kk4 = nkk; wr4 = nwr; w4 = nw; k4 = nk; a4 = na; vv[0] = nv0; vv[1] = nv1; sc = nsc;
;             }
.Lscan_chunk:
	s_and_b32 s24, s30, 1
	s_mul_i32 s4, s24, 0xb200
	s_lshl_b32 s31, s24, 14
	v_add_u32_e32 v10, s4, v84
	v_add_u32_e32 v11, s4, v85
	v_add_u32_e32 v12, s4, v86
	v_mov_b32_e32 v13, s4
	v_add_u32_e32 v14, s31, v87
	ds_read_b128 v[16:19], v10 offset:0
	ds_read_b128 v[20:23], v10 offset:8192
	ds_read_b128 v[24:27], v10 offset:16384
	ds_read_b128 v[28:31], v10 offset:24576
	ds_read_b128 v[32:35], v10 offset:32768
	ds_read_b32 v36, v11 offset:40960
	ds_read_b32 v37, v12 offset:40960
	ds_read_b64 v[38:39], v13 offset:45056
	s_waitcnt lgkmcnt(0)
	s_waitcnt lgkmcnt(6)
	v_pk_mul_f32 v[64:65], v[2:3], v[16:17] op_sel_hi:[1,0]
	v_pk_mul_f32 v[66:67], v[2:3], v[20:21] op_sel_hi:[1,0]
	ds_read_b128 v[40:43], v10 offset:256
	v_pk_fma_f32 v[64:65], v[4:5], v[16:17], v[64:65] op_sel:[0,1,0] op_sel_hi:[1,1,1]
	v_pk_fma_f32 v[66:67], v[4:5], v[20:21], v[66:67] op_sel:[0,1,0] op_sel_hi:[1,1,1]
	ds_read_b128 v[44:47], v10 offset:8448
	v_pk_fma_f32 v[64:65], v[6:7], v[18:19], v[64:65] op_sel_hi:[1,0,1]
	v_pk_fma_f32 v[66:67], v[6:7], v[22:23], v[66:67] op_sel_hi:[1,0,1]
	ds_read_b128 v[48:51], v10 offset:16640
	v_pk_fma_f32 v[64:65], v[8:9], v[18:19], v[64:65] op_sel:[0,1,0] op_sel_hi:[1,1,1]
	v_pk_fma_f32 v[66:67], v[8:9], v[22:23], v[66:67] op_sel:[0,1,0] op_sel_hi:[1,1,1]
	ds_read_b128 v[52:55], v10 offset:24832
	v_add_f32_dpp v78, v65, v64 quad_perm:[1,0,3,2] row_mask:0xf bank_mask:0xf bound_ctrl:1
	ds_read_b128 v[56:59], v10 offset:33024
	ds_read_b32 v60, v11 offset:41088
	v_add_f32_dpp v79, v78, v78 quad_perm:[3,2,1,0] row_mask:0xf bank_mask:0xf bound_ctrl:1
	ds_read_b32 v61, v12 offset:41088
	ds_read_b64 v[62:63], v13 offset:45064
	v_add_f32_dpp v80, v79, v79 row_half_mirror row_mask:0xf bank_mask:0xf bound_ctrl:1
	s_waitcnt lgkmcnt(9)
	v_pk_mul_f32 v[68:69], v[36:37], v[28:29] op_sel_hi:[1,0]
	v_add_f32_dpp v76, v80, v80 row_mirror row_mask:0xf bank_mask:0xf bound_ctrl:1
	v_pk_mul_f32 v[70:71], v[36:37], v[28:29] op_sel:[0,1] op_sel_hi:[1,1]
	v_pk_mul_f32 v[72:73], v[36:37], v[30:31] op_sel_hi:[1,0]
	v_mov_b32_dpp v77, v76 quad_perm:[1,0,3,2] row_mask:0xf bank_mask:0xf bound_ctrl:1
	v_pk_mul_f32 v[74:75], v[36:37], v[30:31] op_sel:[0,1] op_sel_hi:[1,1]
	v_pk_fma_f32 v[68:69], v[2:3], v[24:25], v[68:69] op_sel_hi:[1,0,1]
	v_pk_fma_f32 v[70:71], v[4:5], v[24:25], v[70:71] op_sel:[0,1,0] op_sel_hi:[1,1,1]
	v_pk_fma_f32 v[72:73], v[6:7], v[26:27], v[72:73] op_sel_hi:[1,0,1]
	v_pk_fma_f32 v[74:75], v[8:9], v[26:27], v[74:75] op_sel:[0,1,0] op_sel_hi:[1,1,1]
	v_pk_fma_f32 v[2:3], v[32:33], v[76:77], v[68:69] op_sel_hi:[0,1,1] neg_lo:[1,0,0] neg_hi:[1,0,0]
	v_pk_fma_f32 v[4:5], v[32:33], v[76:77], v[70:71] op_sel:[1,0,0] op_sel_hi:[1,1,1] neg_lo:[1,0,0] neg_hi:[1,0,0]
	s_waitcnt lgkmcnt(8)
	v_mul_f32_e32 v83, v36, v38
	v_add_f32_dpp v81, v67, v66 quad_perm:[1,0,3,2] row_mask:0xf bank_mask:0xf bound_ctrl:1
	v_pk_fma_f32 v[6:7], v[34:35], v[76:77], v[72:73] op_sel_hi:[0,1,1] neg_lo:[1,0,0] neg_hi:[1,0,0]
	v_pk_fma_f32 v[8:9], v[34:35], v[76:77], v[74:75] op_sel:[1,0,0] op_sel_hi:[1,1,1] neg_lo:[1,0,0] neg_hi:[1,0,0]
	v_add_f32_dpp v82, v81, v81 quad_perm:[3,2,1,0] row_mask:0xf bank_mask:0xf bound_ctrl:1
	v_fma_f32 v83, -v76, v39, v83
	v_fmac_f32_e32 v82, 0x3e800000, v83
	ds_write_b32 v14, v82 offset:0
	s_waitcnt lgkmcnt(7)
	v_pk_mul_f32 v[64:65], v[2:3], v[40:41] op_sel_hi:[1,0]
	v_pk_mul_f32 v[66:67], v[2:3], v[44:45] op_sel_hi:[1,0]
	ds_read_b128 v[16:19], v10 offset:512
	v_pk_fma_f32 v[64:65], v[4:5], v[40:41], v[64:65] op_sel:[0,1,0] op_sel_hi:[1,1,1]
	v_pk_fma_f32 v[66:67], v[4:5], v[44:45], v[66:67] op_sel:[0,1,0] op_sel_hi:[1,1,1]
	ds_read_b128 v[20:23], v10 offset:8704
	v_pk_fma_f32 v[64:65], v[6:7], v[42:43], v[64:65] op_sel_hi:[1,0,1]
	v_pk_fma_f32 v[66:67], v[6:7], v[46:47], v[66:67] op_sel_hi:[1,0,1]
	ds_read_b128 v[24:27], v10 offset:16896
	v_pk_fma_f32 v[64:65], v[8:9], v[42:43], v[64:65] op_sel:[0,1,0] op_sel_hi:[1,1,1]
	v_pk_fma_f32 v[66:67], v[8:9], v[46:47], v[66:67] op_sel:[0,1,0] op_sel_hi:[1,1,1]
	ds_read_b128 v[28:31], v10 offset:25088
	v_add_f32_dpp v78, v65, v64 quad_perm:[1,0,3,2] row_mask:0xf bank_mask:0xf bound_ctrl:1
	ds_read_b128 v[32:35], v10 offset:33280
	ds_read_b32 v36, v11 offset:41216
	v_add_f32_dpp v79, v78, v78 quad_perm:[3,2,1,0] row_mask:0xf bank_mask:0xf bound_ctrl:1
	ds_read_b32 v37, v12 offset:41216
	ds_read_b64 v[38:39], v13 offset:45072
	v_add_f32_dpp v80, v79, v79 row_half_mirror row_mask:0xf bank_mask:0xf bound_ctrl:1
	s_waitcnt lgkmcnt(10)
	v_pk_mul_f32 v[68:69], v[60:61], v[52:53] op_sel_hi:[1,0]
	v_add_f32_dpp v76, v80, v80 row_mirror row_mask:0xf bank_mask:0xf bound_ctrl:1
	v_pk_mul_f32 v[70:71], v[60:61], v[52:53] op_sel:[0,1] op_sel_hi:[1,1]
	v_pk_mul_f32 v[72:73], v[60:61], v[54:55] op_sel_hi:[1,0]
	v_mov_b32_dpp v77, v76 quad_perm:[1,0,3,2] row_mask:0xf bank_mask:0xf bound_ctrl:1
	v_pk_mul_f32 v[74:75], v[60:61], v[54:55] op_sel:[0,1] op_sel_hi:[1,1]
	v_pk_fma_f32 v[68:69], v[2:3], v[48:49], v[68:69] op_sel_hi:[1,0,1]
	v_pk_fma_f32 v[70:71], v[4:5], v[48:49], v[70:71] op_sel:[0,1,0] op_sel_hi:[1,1,1]
	v_pk_fma_f32 v[72:73], v[6:7], v[50:51], v[72:73] op_sel_hi:[1,0,1]
	v_pk_fma_f32 v[74:75], v[8:9], v[50:51], v[74:75] op_sel:[0,1,0] op_sel_hi:[1,1,1]
	v_pk_fma_f32 v[2:3], v[56:57], v[76:77], v[68:69] op_sel_hi:[0,1,1] neg_lo:[1,0,0] neg_hi:[1,0,0]
	v_pk_fma_f32 v[4:5], v[56:57], v[76:77], v[70:71] op_sel:[1,0,0] op_sel_hi:[1,1,1] neg_lo:[1,0,0] neg_hi:[1,0,0]
	s_waitcnt lgkmcnt(9)
; #define LAS __attribute__((address_space(3)))
; template <int CTRL> __device__ __forceinline__ float dppf(float x) { return __builtin_bit_cast(float, __builtin_amdgcn_mov_dpp(__builtin_bit_cast(int, x), CTRL, 0xf, 0xf, true)); }
; __device__ __forceinline__ float sum16(float x) { x = sum8(x); x += dppf<0x140>(x); return x; }
; __device__ __forceinline__ void rwkv_item(LAS unsigned char* lds, int l, const bf16_t* PROJ, const bf16_t* LO, bf16_t* YR, float* BON, int b, int h, int qv) {
;     ...
;             for (int t = 0; t < CH; ++t) {
;                 const int tn = (t + 1) & (CH - 1);
;                 const LAS float* pn = pk + tn * 64;
;                 const f32x4 nkk = *(const LAS f32x4*)(pn), nwr = *(const LAS f32x4*)(pn + 2048), nw = *(const LAS f32x4*)(pn + 4096), nk = *(const LAS f32x4*)(pn + 6144), na = *(const LAS f32x4*)(pn + 8192);
;                 const float nv0 = pv[tn * 32], nv1 = pv[tn * 32 + 4]; const f32x2 nsc = *(const LAS f32x2*)(ps + 2 * tn);
;                 float sa[2], yp[2];
; #pragma unroll
;                 for (int c = 0; c < 2; ++c) { const f32x2 pa = S23[c] * kk4.hi + S01[c] * kk4.lo, pb = S23[c] * wr4.hi + S01[c] * wr4.lo; sa[c] = pa.x + pa.y; yp[c] = pb.x + pb.y; }
; #pragma unroll
;                 for (int c = 0; c < 2; ++c) { sa[c] = sum16(sa[c]); yp[c] += dppf<0xB1>(yp[c]); yp[c] += dppf<0x4E>(yp[c]); }
; #pragma unroll
;                 for (int c = 0; c < 2; ++c) {
;                     S01[c] = S01[c] * w4.lo + (k4.lo * vv[c] - a4.lo * sa[c]);
;                     S23[c] = S23[c] * w4.hi + (k4.hi * vv[c] - a4.hi * sa[c]);
;                     py[(t * 32 + 4 * c) * 4] = yp[c] + 0.25f * (vv[c] * sc.x - sa[c] * sc.y);
;                 }
;                 kk4 = nkk; wr4 = nwr; w4 = nw; k4 = nk; a4 = na; vv[0] = nv0; vv[1] = nv1; sc = nsc;
;             }
	v_mul_f32_e32 v83, v60, v62
	v_add_f32_dpp v81, v67, v66 quad_perm:[1,0,3,2] row_mask:0xf bank_mask:0xf bound_ctrl:1
	v_pk_fma_f32 v[6:7], v[58:59], v[76:77], v[72:73] op_sel_hi:[0,1,1] neg_lo:[1,0,0] neg_hi:[1,0,0]
	v_pk_fma_f32 v[8:9], v[58:59], v[76:77], v[74:75] op_sel:[1,0,0] op_sel_hi:[1,1,1] neg_lo:[1,0,0] neg_hi:[1,0,0]
	v_add_f32_dpp v82, v81, v81 quad_perm:[3,2,1,0] row_mask:0xf bank_mask:0xf bound_ctrl:1
	v_fma_f32 v83, -v76, v63, v83
	v_fmac_f32_e32 v82, 0x3e800000, v83
	ds_write_b32 v14, v82 offset:512
	s_waitcnt lgkmcnt(7)
	v_pk_mul_f32 v[64:65], v[2:3], v[16:17] op_sel_hi:[1,0]
	v_pk_mul_f32 v[66:67], v[2:3], v[20:21] op_sel_hi:[1,0]
	ds_read_b128 v[40:43], v10 offset:768
	v_pk_fma_f32 v[64:65], v[4:5], v[16:17], v[64:65] op_sel:[0,1,0] op_sel_hi:[1,1,1]
	v_pk_fma_f32 v[66:67], v[4:5], v[20:21], v[66:67] op_sel:[0,1,0] op_sel_hi:[1,1,1]
	ds_read_b128 v[44:47], v10 offset:8960
	v_pk_fma_f32 v[64:65], v[6:7], v[18:19], v[64:65] op_sel_hi:[1,0,1]
	v_pk_fma_f32 v[66:67], v[6:7], v[22:23], v[66:67] op_sel_hi:[1,0,1]
	ds_read_b128 v[48:51], v10 offset:17152
	v_pk_fma_f32 v[64:65], v[8:9], v[18:19], v[64:65] op_sel:[0,1,0] op_sel_hi:[1,1,1]
	v_pk_fma_f32 v[66:67], v[8:9], v[22:23], v[66:67] op_sel:[0,1,0] op_sel_hi:[1,1,1]
	ds_read_b128 v[52:55], v10 offset:25344
	v_add_f32_dpp v78, v65, v64 quad_perm:[1,0,3,2] row_mask:0xf bank_mask:0xf bound_ctrl:1
	ds_read_b128 v[56:59], v10 offset:33536
	ds_read_b32 v60, v11 offset:41344
	v_add_f32_dpp v79, v78, v78 quad_perm:[3,2,1,0] row_mask:0xf bank_mask:0xf bound_ctrl:1
	ds_read_b32 v61, v12 offset:41344
	ds_read_b64 v[62:63], v13 offset:45080
	v_add_f32_dpp v80, v79, v79 row_half_mirror row_mask:0xf bank_mask:0xf bound_ctrl:1
	s_waitcnt lgkmcnt(10)
	v_pk_mul_f32 v[68:69], v[36:37], v[28:29] op_sel_hi:[1,0]
	v_add_f32_dpp v76, v80, v80 row_mirror row_mask:0xf bank_mask:0xf bound_ctrl:1
	v_pk_mul_f32 v[70:71], v[36:37], v[28:29] op_sel:[0,1] op_sel_hi:[1,1]
	v_pk_mul_f32 v[72:73], v[36:37], v[30:31] op_sel_hi:[1,0]
	v_mov_b32_dpp v77, v76 quad_perm:[1,0,3,2] row_mask:0xf bank_mask:0xf bound_ctrl:1
	v_pk_mul_f32 v[74:75], v[36:37], v[30:31] op_sel:[0,1] op_sel_hi:[1,1]
	v_pk_fma_f32 v[68:69], v[2:3], v[24:25], v[68:69] op_sel_hi:[1,0,1]
	v_pk_fma_f32 v[70:71], v[4:5], v[24:25], v[70:71] op_sel:[0,1,0] op_sel_hi:[1,1,1]
	v_pk_fma_f32 v[72:73], v[6:7], v[26:27], v[72:73] op_sel_hi:[1,0,1]
	v_pk_fma_f32 v[74:75], v[8:9], v[26:27], v[74:75] op_sel:[0,1,0] op_sel_hi:[1,1,1]
	v_pk_fma_f32 v[2:3], v[32:33], v[76:77], v[68:69] op_sel_hi:[0,1,1] neg_lo:[1,0,0] neg_hi:[1,0,0]
	v_pk_fma_f32 v[4:5], v[32:33], v[76:77], v[70:71] op_sel:[1,0,0] op_sel_hi:[1,1,1] neg_lo:[1,0,0] neg_hi:[1,0,0]
	s_waitcnt lgkmcnt(9)
	v_mul_f32_e32 v83, v36, v38
	v_add_f32_dpp v81, v67, v66 quad_perm:[1,0,3,2] row_mask:0xf bank_mask:0xf bound_ctrl:1
	v_pk_fma_f32 v[6:7], v[34:35], v[76:77], v[72:73] op_sel_hi:[0,1,1] neg_lo:[1,0,0] neg_hi:[1,0,0]
	v_pk_fma_f32 v[8:9], v[34:35], v[76:77], v[74:75] op_sel:[1,0,0] op_sel_hi:[1,1,1] neg_lo:[1,0,0] neg_hi:[1,0,0]
	v_add_f32_dpp v82, v81, v81 quad_perm:[3,2,1,0] row_mask:0xf bank_mask:0xf bound_ctrl:1
	v_fma_f32 v83, -v76, v39, v83
	v_fmac_f32_e32 v82, 0x3e800000, v83
	ds_write_b32 v14, v82 offset:1024
	s_waitcnt lgkmcnt(7)
	v_pk_mul_f32 v[64:65], v[2:3], v[40:41] op_sel_hi:[1,0]
	v_pk_mul_f32 v[66:67], v[2:3], v[44:45] op_sel_hi:[1,0]
	ds_read_b128 v[16:19], v10 offset:1024
	v_pk_fma_f32 v[64:65], v[4:5], v[40:41], v[64:65] op_sel:[0,1,0] op_sel_hi:[1,1,1]
	v_pk_fma_f32 v[66:67], v[4:5], v[44:45], v[66:67] op_sel:[0,1,0] op_sel_hi:[1,1,1]
	ds_read_b128 v[20:23], v10 offset:9216
	v_pk_fma_f32 v[64:65], v[6:7], v[42:43], v[64:65] op_sel_hi:[1,0,1]
	v_pk_fma_f32 v[66:67], v[6:7], v[46:47], v[66:67] op_sel_hi:[1,0,1]
	ds_read_b128 v[24:27], v10 offset:17408
	v_pk_fma_f32 v[64:65], v[8:9], v[42:43], v[64:65] op_sel:[0,1,0] op_sel_hi:[1,1,1]
	v_pk_fma_f32 v[66:67], v[8:9], v[46:47], v[66:67] op_sel:[0,1,0] op_sel_hi:[1,1,1]
	ds_read_b128 v[28:31], v10 offset:25600
	v_add_f32_dpp v78, v65, v64 quad_perm:[1,0,3,2] row_mask:0xf bank_mask:0xf bound_ctrl:1
	ds_read_b128 v[32:35], v10 offset:33792
	ds_read_b32 v36, v11 offset:41472
	v_add_f32_dpp v79, v78, v78 quad_perm:[3,2,1,0] row_mask:0xf bank_mask:0xf bound_ctrl:1
	ds_read_b32 v37, v12 offset:41472
	ds_read_b64 v[38:39], v13 offset:45088
	v_add_f32_dpp v80, v79, v79 row_half_mirror row_mask:0xf bank_mask:0xf bound_ctrl:1
	s_waitcnt lgkmcnt(10)
	v_pk_mul_f32 v[68:69], v[60:61], v[52:53] op_sel_hi:[1,0]
	v_add_f32_dpp v76, v80, v80 row_mirror row_mask:0xf bank_mask:0xf bound_ctrl:1
	v_pk_mul_f32 v[70:71], v[60:61], v[52:53] op_sel:[0,1] op_sel_hi:[1,1]
	v_pk_mul_f32 v[72:73], v[60:61], v[54:55] op_sel_hi:[1,0]
	v_mov_b32_dpp v77, v76 quad_perm:[1,0,3,2] row_mask:0xf bank_mask:0xf bound_ctrl:1
	v_pk_mul_f32 v[74:75], v[60:61], v[54:55] op_sel:[0,1] op_sel_hi:[1,1]
	v_pk_fma_f32 v[68:69], v[2:3], v[48:49], v[68:69] op_sel_hi:[1,0,1]
	v_pk_fma_f32 v[70:71], v[4:5], v[48:49], v[70:71] op_sel:[0,1,0] op_sel_hi:[1,1,1]
	v_pk_fma_f32 v[72:73], v[6:7], v[50:51], v[72:73] op_sel_hi:[1,0,1]
	v_pk_fma_f32 v[74:75], v[8:9], v[50:51], v[74:75] op_sel:[0,1,0] op_sel_hi:[1,1,1]
	v_pk_fma_f32 v[2:3], v[56:57], v[76:77], v[68:69] op_sel_hi:[0,1,1] neg_lo:[1,0,0] neg_hi:[1,0,0]
	v_pk_fma_f32 v[4:5], v[56:57], v[76:77], v[70:71] op_sel:[1,0,0] op_sel_hi:[1,1,1] neg_lo:[1,0,0] neg_hi:[1,0,0]
	s_waitcnt lgkmcnt(9)
; #define LAS __attribute__((address_space(3)))
; template <int CTRL> __device__ __forceinline__ float dppf(float x) { return __builtin_bit_cast(float, __builtin_amdgcn_mov_dpp(__builtin_bit_cast(int, x), CTRL, 0xf, 0xf, true)); }
; __device__ __forceinline__ float sum16(float x) { x = sum8(x); x += dppf<0x140>(x); return x; }
; __device__ __forceinline__ void rwkv_item(LAS unsigned char* lds, int l, const bf16_t* PROJ, const bf16_t* LO, bf16_t* YR, float* BON, int b, int h, int qv) {
;     ...
;             for (int t = 0; t < CH; ++t) {
;                 const int tn = (t + 1) & (CH - 1);
;                 const LAS float* pn = pk + tn * 64;
;                 const f32x4 nkk = *(const LAS f32x4*)(pn), nwr = *(const LAS f32x4*)(pn + 2048), nw = *(const LAS f32x4*)(pn + 4096), nk = *(const LAS f32x4*)(pn + 6144), na = *(const LAS f32x4*)(pn + 8192);
;                 const float nv0 = pv[tn * 32], nv1 = pv[tn * 32 + 4]; const f32x2 nsc = *(const LAS f32x2*)(ps + 2 * tn);
;                 float sa[2], yp[2];
; #pragma unroll
;                 for (int c = 0; c < 2; ++c) { const f32x2 pa = S23[c] * kk4.hi + S01[c] * kk4.lo, pb = S23[c] * wr4.hi + S01[c] * wr4.lo; sa[c] = pa.x + pa.y; yp[c] = pb.x + pb.y; }
; #pragma unroll
;                 for (int c = 0; c < 2; ++c) { sa[c] = sum16(sa[c]); yp[c] += dppf<0xB1>(yp[c]); yp[c] += dppf<0x4E>(yp[c]); }
; #pragma unroll
;                 for (int c = 0; c < 2; ++c) {
;                     S01[c] = S01[c] * w4.lo + (k4.lo * vv[c] - a4.lo * sa[c]);
;                     S23[c] = S23[c] * w4.hi + (k4.hi * vv[c] - a4.hi * sa[c]);
;                     py[(t * 32 + 4 * c) * 4] = yp[c] + 0.25f * (vv[c] * sc.x - sa[c] * sc.y);
;                 }
;                 kk4 = nkk; wr4 = nwr; w4 = nw; k4 = nk; a4 = na; vv[0] = nv0; vv[1] = nv1; sc = nsc;
;             }
	v_mul_f32_e32 v83, v60, v62
	v_add_f32_dpp v81, v67, v66 quad_perm:[1,0,3,2] row_mask:0xf bank_mask:0xf bound_ctrl:1
	v_pk_fma_f32 v[6:7], v[58:59], v[76:77], v[72:73] op_sel_hi:[0,1,1] neg_lo:[1,0,0] neg_hi:[1,0,0]
	v_pk_fma_f32 v[8:9], v[58:59], v[76:77], v[74:75] op_sel:[1,0,0] op_sel_hi:[1,1,1] neg_lo:[1,0,0] neg_hi:[1,0,0]
	v_add_f32_dpp v82, v81, v81 quad_perm:[3,2,1,0] row_mask:0xf bank_mask:0xf bound_ctrl:1
	v_fma_f32 v83, -v76, v63, v83
	v_fmac_f32_e32 v82, 0x3e800000, v83
	ds_write_b32 v14, v82 offset:1536
	s_waitcnt lgkmcnt(7)
	v_pk_mul_f32 v[64:65], v[2:3], v[16:17] op_sel_hi:[1,0]
	v_pk_mul_f32 v[66:67], v[2:3], v[20:21] op_sel_hi:[1,0]
	ds_read_b128 v[40:43], v10 offset:1280
	v_pk_fma_f32 v[64:65], v[4:5], v[16:17], v[64:65] op_sel:[0,1,0] op_sel_hi:[1,1,1]
	v_pk_fma_f32 v[66:67], v[4:5], v[20:21], v[66:67] op_sel:[0,1,0] op_sel_hi:[1,1,1]
	ds_read_b128 v[44:47], v10 offset:9472
	v_pk_fma_f32 v[64:65], v[6:7], v[18:19], v[64:65] op_sel_hi:[1,0,1]
	v_pk_fma_f32 v[66:67], v[6:7], v[22:23], v[66:67] op_sel_hi:[1,0,1]
	ds_read_b128 v[48:51], v10 offset:17664
	v_pk_fma_f32 v[64:65], v[8:9], v[18:19], v[64:65] op_sel:[0,1,0] op_sel_hi:[1,1,1]
	v_pk_fma_f32 v[66:67], v[8:9], v[22:23], v[66:67] op_sel:[0,1,0] op_sel_hi:[1,1,1]
	ds_read_b128 v[52:55], v10 offset:25856
	v_add_f32_dpp v78, v65, v64 quad_perm:[1,0,3,2] row_mask:0xf bank_mask:0xf bound_ctrl:1
	ds_read_b128 v[56:59], v10 offset:34048
	ds_read_b32 v60, v11 offset:41600
	v_add_f32_dpp v79, v78, v78 quad_perm:[3,2,1,0] row_mask:0xf bank_mask:0xf bound_ctrl:1
	ds_read_b32 v61, v12 offset:41600
	ds_read_b64 v[62:63], v13 offset:45096
	v_add_f32_dpp v80, v79, v79 row_half_mirror row_mask:0xf bank_mask:0xf bound_ctrl:1
	s_waitcnt lgkmcnt(10)
	v_pk_mul_f32 v[68:69], v[36:37], v[28:29] op_sel_hi:[1,0]
	v_add_f32_dpp v76, v80, v80 row_mirror row_mask:0xf bank_mask:0xf bound_ctrl:1
	v_pk_mul_f32 v[70:71], v[36:37], v[28:29] op_sel:[0,1] op_sel_hi:[1,1]
	v_pk_mul_f32 v[72:73], v[36:37], v[30:31] op_sel_hi:[1,0]
	v_mov_b32_dpp v77, v76 quad_perm:[1,0,3,2] row_mask:0xf bank_mask:0xf bound_ctrl:1
	v_pk_mul_f32 v[74:75], v[36:37], v[30:31] op_sel:[0,1] op_sel_hi:[1,1]
	v_pk_fma_f32 v[68:69], v[2:3], v[24:25], v[68:69] op_sel_hi:[1,0,1]
	v_pk_fma_f32 v[70:71], v[4:5], v[24:25], v[70:71] op_sel:[0,1,0] op_sel_hi:[1,1,1]
	v_pk_fma_f32 v[72:73], v[6:7], v[26:27], v[72:73] op_sel_hi:[1,0,1]
	v_pk_fma_f32 v[74:75], v[8:9], v[26:27], v[74:75] op_sel:[0,1,0] op_sel_hi:[1,1,1]
	v_pk_fma_f32 v[2:3], v[32:33], v[76:77], v[68:69] op_sel_hi:[0,1,1] neg_lo:[1,0,0] neg_hi:[1,0,0]
	v_pk_fma_f32 v[4:5], v[32:33], v[76:77], v[70:71] op_sel:[1,0,0] op_sel_hi:[1,1,1] neg_lo:[1,0,0] neg_hi:[1,0,0]
	s_waitcnt lgkmcnt(9)
	v_mul_f32_e32 v83, v36, v38
	v_add_f32_dpp v81, v67, v66 quad_perm:[1,0,3,2] row_mask:0xf bank_mask:0xf bound_ctrl:1
	v_pk_fma_f32 v[6:7], v[34:35], v[76:77], v[72:73] op_sel_hi:[0,1,1] neg_lo:[1,0,0] neg_hi:[1,0,0]
	v_pk_fma_f32 v[8:9], v[34:35], v[76:77], v[74:75] op_sel:[1,0,0] op_sel_hi:[1,1,1] neg_lo:[1,0,0] neg_hi:[1,0,0]
	v_add_f32_dpp v82, v81, v81 quad_perm:[3,2,1,0] row_mask:0xf bank_mask:0xf bound_ctrl:1
	v_fma_f32 v83, -v76, v39, v83
	v_fmac_f32_e32 v82, 0x3e800000, v83
	ds_write_b32 v14, v82 offset:2048
	s_waitcnt lgkmcnt(7)
	v_pk_mul_f32 v[64:65], v[2:3], v[40:41] op_sel_hi:[1,0]
	v_pk_mul_f32 v[66:67], v[2:3], v[44:45] op_sel_hi:[1,0]
	ds_read_b128 v[16:19], v10 offset:1536
	v_pk_fma_f32 v[64:65], v[4:5], v[40:41], v[64:65] op_sel:[0,1,0] op_sel_hi:[1,1,1]
	v_pk_fma_f32 v[66:67], v[4:5], v[44:45], v[66:67] op_sel:[0,1,0] op_sel_hi:[1,1,1]
	ds_read_b128 v[20:23], v10 offset:9728
	v_pk_fma_f32 v[64:65], v[6:7], v[42:43], v[64:65] op_sel_hi:[1,0,1]
	v_pk_fma_f32 v[66:67], v[6:7], v[46:47], v[66:67] op_sel_hi:[1,0,1]
	ds_read_b128 v[24:27], v10 offset:17920
	v_pk_fma_f32 v[64:65], v[8:9], v[42:43], v[64:65] op_sel:[0,1,0] op_sel_hi:[1,1,1]
	v_pk_fma_f32 v[66:67], v[8:9], v[46:47], v[66:67] op_sel:[0,1,0] op_sel_hi:[1,1,1]
	ds_read_b128 v[28:31], v10 offset:26112
	v_add_f32_dpp v78, v65, v64 quad_perm:[1,0,3,2] row_mask:0xf bank_mask:0xf bound_ctrl:1
	ds_read_b128 v[32:35], v10 offset:34304
	ds_read_b32 v36, v11 offset:41728
	v_add_f32_dpp v79, v78, v78 quad_perm:[3,2,1,0] row_mask:0xf bank_mask:0xf bound_ctrl:1
	ds_read_b32 v37, v12 offset:41728
	ds_read_b64 v[38:39], v13 offset:45104
	v_add_f32_dpp v80, v79, v79 row_half_mirror row_mask:0xf bank_mask:0xf bound_ctrl:1
	s_waitcnt lgkmcnt(10)
	v_pk_mul_f32 v[68:69], v[60:61], v[52:53] op_sel_hi:[1,0]
	v_add_f32_dpp v76, v80, v80 row_mirror row_mask:0xf bank_mask:0xf bound_ctrl:1
	v_pk_mul_f32 v[70:71], v[60:61], v[52:53] op_sel:[0,1] op_sel_hi:[1,1]
	v_pk_mul_f32 v[72:73], v[60:61], v[54:55] op_sel_hi:[1,0]
	v_mov_b32_dpp v77, v76 quad_perm:[1,0,3,2] row_mask:0xf bank_mask:0xf bound_ctrl:1
	v_pk_mul_f32 v[74:75], v[60:61], v[54:55] op_sel:[0,1] op_sel_hi:[1,1]
	v_pk_fma_f32 v[68:69], v[2:3], v[48:49], v[68:69] op_sel_hi:[1,0,1]
	v_pk_fma_f32 v[70:71], v[4:5], v[48:49], v[70:71] op_sel:[0,1,0] op_sel_hi:[1,1,1]
	v_pk_fma_f32 v[72:73], v[6:7], v[50:51], v[72:73] op_sel_hi:[1,0,1]
	v_pk_fma_f32 v[74:75], v[8:9], v[50:51], v[74:75] op_sel:[0,1,0] op_sel_hi:[1,1,1]
	v_pk_fma_f32 v[2:3], v[56:57], v[76:77], v[68:69] op_sel_hi:[0,1,1] neg_lo:[1,0,0] neg_hi:[1,0,0]
	v_pk_fma_f32 v[4:5], v[56:57], v[76:77], v[70:71] op_sel:[1,0,0] op_sel_hi:[1,1,1] neg_lo:[1,0,0] neg_hi:[1,0,0]
	s_waitcnt lgkmcnt(9)
; #define LAS __attribute__((address_space(3)))
; template <int CTRL> __device__ __forceinline__ float dppf(float x) { return __builtin_bit_cast(float, __builtin_amdgcn_mov_dpp(__builtin_bit_cast(int, x), CTRL, 0xf, 0xf, true)); }
; __device__ __forceinline__ float sum16(float x) { x = sum8(x); x += dppf<0x140>(x); return x; }
; __device__ __forceinline__ void rwkv_item(LAS unsigned char* lds, int l, const bf16_t* PROJ, const bf16_t* LO, bf16_t* YR, float* BON, int b, int h, int qv) {
;     ...
;             for (int t = 0; t < CH; ++t) {
;                 const int tn = (t + 1) & (CH - 1);
;                 const LAS float* pn = pk + tn * 64;
;                 const f32x4 nkk = *(const LAS f32x4*)(pn), nwr = *(const LAS f32x4*)(pn + 2048), nw = *(const LAS f32x4*)(pn + 4096), nk = *(const LAS f32x4*)(pn + 6144), na = *(const LAS f32x4*)(pn + 8192);
;                 const float nv0 = pv[tn * 32], nv1 = pv[tn * 32 + 4]; const f32x2 nsc = *(const LAS f32x2*)(ps + 2 * tn);
;                 float sa[2], yp[2];
; #pragma unroll
;                 for (int c = 0; c < 2; ++c) { const f32x2 pa = S23[c] * kk4.hi + S01[c] * kk4.lo, pb = S23[c] * wr4.hi + S01[c] * wr4.lo; sa[c] = pa.x + pa.y; yp[c] = pb.x + pb.y; }
; #pragma unroll
;                 for (int c = 0; c < 2; ++c) { sa[c] = sum16(sa[c]); yp[c] += dppf<0xB1>(yp[c]); yp[c] += dppf<0x4E>(yp[c]); }
; #pragma unroll
;                 for (int c = 0; c < 2; ++c) {
;                     S01[c] = S01[c] * w4.lo + (k4.lo * vv[c] - a4.lo * sa[c]);
;                     S23[c] = S23[c] * w4.hi + (k4.hi * vv[c] - a4.hi * sa[c]);
;                     py[(t * 32 + 4 * c) * 4] = yp[c] + 0.25f * (vv[c] * sc.x - sa[c] * sc.y);
;                 }
;                 kk4 = nkk; wr4 = nwr; w4 = nw; k4 = nk; a4 = na; vv[0] = nv0; vv[1] = nv1; sc = nsc;
;             }
	v_mul_f32_e32 v83, v60, v62
	v_add_f32_dpp v81, v67, v66 quad_perm:[1,0,3,2] row_mask:0xf bank_mask:0xf bound_ctrl:1
	v_pk_fma_f32 v[6:7], v[58:59], v[76:77], v[72:73] op_sel_hi:[0,1,1] neg_lo:[1,0,0] neg_hi:[1,0,0]
	v_pk_fma_f32 v[8:9], v[58:59], v[76:77], v[74:75] op_sel:[1,0,0] op_sel_hi:[1,1,1] neg_lo:[1,0,0] neg_hi:[1,0,0]
	v_add_f32_dpp v82, v81, v81 quad_perm:[3,2,1,0] row_mask:0xf bank_mask:0xf bound_ctrl:1
	v_fma_f32 v83, -v76, v63, v83
	v_fmac_f32_e32 v82, 0x3e800000, v83
	ds_write_b32 v14, v82 offset:2560
	s_waitcnt lgkmcnt(7)
	v_pk_mul_f32 v[64:65], v[2:3], v[16:17] op_sel_hi:[1,0]
	v_pk_mul_f32 v[66:67], v[2:3], v[20:21] op_sel_hi:[1,0]
	ds_read_b128 v[40:43], v10 offset:1792
	v_pk_fma_f32 v[64:65], v[4:5], v[16:17], v[64:65] op_sel:[0,1,0] op_sel_hi:[1,1,1]
	v_pk_fma_f32 v[66:67], v[4:5], v[20:21], v[66:67] op_sel:[0,1,0] op_sel_hi:[1,1,1]
	ds_read_b128 v[44:47], v10 offset:9984
	v_pk_fma_f32 v[64:65], v[6:7], v[18:19], v[64:65] op_sel_hi:[1,0,1]
	v_pk_fma_f32 v[66:67], v[6:7], v[22:23], v[66:67] op_sel_hi:[1,0,1]
	ds_read_b128 v[48:51], v10 offset:18176
	v_pk_fma_f32 v[64:65], v[8:9], v[18:19], v[64:65] op_sel:[0,1,0] op_sel_hi:[1,1,1]
	v_pk_fma_f32 v[66:67], v[8:9], v[22:23], v[66:67] op_sel:[0,1,0] op_sel_hi:[1,1,1]
	ds_read_b128 v[52:55], v10 offset:26368
	v_add_f32_dpp v78, v65, v64 quad_perm:[1,0,3,2] row_mask:0xf bank_mask:0xf bound_ctrl:1
	ds_read_b128 v[56:59], v10 offset:34560
	ds_read_b32 v60, v11 offset:41856
	v_add_f32_dpp v79, v78, v78 quad_perm:[3,2,1,0] row_mask:0xf bank_mask:0xf bound_ctrl:1
	ds_read_b32 v61, v12 offset:41856
	ds_read_b64 v[62:63], v13 offset:45112
	v_add_f32_dpp v80, v79, v79 row_half_mirror row_mask:0xf bank_mask:0xf bound_ctrl:1
	s_waitcnt lgkmcnt(10)
	v_pk_mul_f32 v[68:69], v[36:37], v[28:29] op_sel_hi:[1,0]
	v_add_f32_dpp v76, v80, v80 row_mirror row_mask:0xf bank_mask:0xf bound_ctrl:1
	v_pk_mul_f32 v[70:71], v[36:37], v[28:29] op_sel:[0,1] op_sel_hi:[1,1]
	v_pk_mul_f32 v[72:73], v[36:37], v[30:31] op_sel_hi:[1,0]
	v_mov_b32_dpp v77, v76 quad_perm:[1,0,3,2] row_mask:0xf bank_mask:0xf bound_ctrl:1
	v_pk_mul_f32 v[74:75], v[36:37], v[30:31] op_sel:[0,1] op_sel_hi:[1,1]
	v_pk_fma_f32 v[68:69], v[2:3], v[24:25], v[68:69] op_sel_hi:[1,0,1]
	v_pk_fma_f32 v[70:71], v[4:5], v[24:25], v[70:71] op_sel:[0,1,0] op_sel_hi:[1,1,1]
	v_pk_fma_f32 v[72:73], v[6:7], v[26:27], v[72:73] op_sel_hi:[1,0,1]
	v_pk_fma_f32 v[74:75], v[8:9], v[26:27], v[74:75] op_sel:[0,1,0] op_sel_hi:[1,1,1]
	v_pk_fma_f32 v[2:3], v[32:33], v[76:77], v[68:69] op_sel_hi:[0,1,1] neg_lo:[1,0,0] neg_hi:[1,0,0]
	v_pk_fma_f32 v[4:5], v[32:33], v[76:77], v[70:71] op_sel:[1,0,0] op_sel_hi:[1,1,1] neg_lo:[1,0,0] neg_hi:[1,0,0]
	s_waitcnt lgkmcnt(9)
	v_mul_f32_e32 v83, v36, v38
	v_add_f32_dpp v81, v67, v66 quad_perm:[1,0,3,2] row_mask:0xf bank_mask:0xf bound_ctrl:1
	v_pk_fma_f32 v[6:7], v[34:35], v[76:77], v[72:73] op_sel_hi:[0,1,1] neg_lo:[1,0,0] neg_hi:[1,0,0]
	v_pk_fma_f32 v[8:9], v[34:35], v[76:77], v[74:75] op_sel:[1,0,0] op_sel_hi:[1,1,1] neg_lo:[1,0,0] neg_hi:[1,0,0]
	v_add_f32_dpp v82, v81, v81 quad_perm:[3,2,1,0] row_mask:0xf bank_mask:0xf bound_ctrl:1
	v_fma_f32 v83, -v76, v39, v83
	v_fmac_f32_e32 v82, 0x3e800000, v83
	ds_write_b32 v14, v82 offset:3072
	s_waitcnt lgkmcnt(7)
	v_pk_mul_f32 v[64:65], v[2:3], v[40:41] op_sel_hi:[1,0]
	v_pk_mul_f32 v[66:67], v[2:3], v[44:45] op_sel_hi:[1,0]
	ds_read_b128 v[16:19], v10 offset:2048
	v_pk_fma_f32 v[64:65], v[4:5], v[40:41], v[64:65] op_sel:[0,1,0] op_sel_hi:[1,1,1]
	v_pk_fma_f32 v[66:67], v[4:5], v[44:45], v[66:67] op_sel:[0,1,0] op_sel_hi:[1,1,1]
	ds_read_b128 v[20:23], v10 offset:10240
	v_pk_fma_f32 v[64:65], v[6:7], v[42:43], v[64:65] op_sel_hi:[1,0,1]
	v_pk_fma_f32 v[66:67], v[6:7], v[46:47], v[66:67] op_sel_hi:[1,0,1]
	ds_read_b128 v[24:27], v10 offset:18432
	v_pk_fma_f32 v[64:65], v[8:9], v[42:43], v[64:65] op_sel:[0,1,0] op_sel_hi:[1,1,1]
	v_pk_fma_f32 v[66:67], v[8:9], v[46:47], v[66:67] op_sel:[0,1,0] op_sel_hi:[1,1,1]
	ds_read_b128 v[28:31], v10 offset:26624
	v_add_f32_dpp v78, v65, v64 quad_perm:[1,0,3,2] row_mask:0xf bank_mask:0xf bound_ctrl:1
	ds_read_b128 v[32:35], v10 offset:34816
	ds_read_b32 v36, v11 offset:41984
	v_add_f32_dpp v79, v78, v78 quad_perm:[3,2,1,0] row_mask:0xf bank_mask:0xf bound_ctrl:1
	ds_read_b32 v37, v12 offset:41984
	ds_read_b64 v[38:39], v13 offset:45120
	v_add_f32_dpp v80, v79, v79 row_half_mirror row_mask:0xf bank_mask:0xf bound_ctrl:1
	s_waitcnt lgkmcnt(10)
	v_pk_mul_f32 v[68:69], v[60:61], v[52:53] op_sel_hi:[1,0]
	v_add_f32_dpp v76, v80, v80 row_mirror row_mask:0xf bank_mask:0xf bound_ctrl:1
	v_pk_mul_f32 v[70:71], v[60:61], v[52:53] op_sel:[0,1] op_sel_hi:[1,1]
	v_pk_mul_f32 v[72:73], v[60:61], v[54:55] op_sel_hi:[1,0]
	v_mov_b32_dpp v77, v76 quad_perm:[1,0,3,2] row_mask:0xf bank_mask:0xf bound_ctrl:1
	v_pk_mul_f32 v[74:75], v[60:61], v[54:55] op_sel:[0,1] op_sel_hi:[1,1]
	v_pk_fma_f32 v[68:69], v[2:3], v[48:49], v[68:69] op_sel_hi:[1,0,1]
	v_pk_fma_f32 v[70:71], v[4:5], v[48:49], v[70:71] op_sel:[0,1,0] op_sel_hi:[1,1,1]
	v_pk_fma_f32 v[72:73], v[6:7], v[50:51], v[72:73] op_sel_hi:[1,0,1]
	v_pk_fma_f32 v[74:75], v[8:9], v[50:51], v[74:75] op_sel:[0,1,0] op_sel_hi:[1,1,1]
	v_pk_fma_f32 v[2:3], v[56:57], v[76:77], v[68:69] op_sel_hi:[0,1,1] neg_lo:[1,0,0] neg_hi:[1,0,0]
	v_pk_fma_f32 v[4:5], v[56:57], v[76:77], v[70:71] op_sel:[1,0,0] op_sel_hi:[1,1,1] neg_lo:[1,0,0] neg_hi:[1,0,0]
	s_waitcnt lgkmcnt(9)
; #define LAS __attribute__((address_space(3)))
; template <int CTRL> __device__ __forceinline__ float dppf(float x) { return __builtin_bit_cast(float, __builtin_amdgcn_mov_dpp(__builtin_bit_cast(int, x), CTRL, 0xf, 0xf, true)); }
; __device__ __forceinline__ float sum16(float x) { x = sum8(x); x += dppf<0x140>(x); return x; }
; __device__ __forceinline__ void rwkv_item(LAS unsigned char* lds, int l, const bf16_t* PROJ, const bf16_t* LO, bf16_t* YR, float* BON, int b, int h, int qv) {
;     ...
;             for (int t = 0; t < CH; ++t) {
;                 const int tn = (t + 1) & (CH - 1);
;                 const LAS float* pn = pk + tn * 64;
;                 const f32x4 nkk = *(const LAS f32x4*)(pn), nwr = *(const LAS f32x4*)(pn + 2048), nw = *(const LAS f32x4*)(pn + 4096), nk = *(const LAS f32x4*)(pn + 6144), na = *(const LAS f32x4*)(pn + 8192);
;                 const float nv0 = pv[tn * 32], nv1 = pv[tn * 32 + 4]; const f32x2 nsc = *(const LAS f32x2*)(ps + 2 * tn);
;                 float sa[2], yp[2];
; #pragma unroll
;                 for (int c = 0; c < 2; ++c) { const f32x2 pa = S23[c] * kk4.hi + S01[c] * kk4.lo, pb = S23[c] * wr4.hi + S01[c] * wr4.lo; sa[c] = pa.x + pa.y; yp[c] = pb.x + pb.y; }
; #pragma unroll
;                 for (int c = 0; c < 2; ++c) { sa[c] = sum16(sa[c]); yp[c] += dppf<0xB1>(yp[c]); yp[c] += dppf<0x4E>(yp[c]); }
; #pragma unroll
;                 for (int c = 0; c < 2; ++c) {
;                     S01[c] = S01[c] * w4.lo + (k4.lo * vv[c] - a4.lo * sa[c]);
;                     S23[c] = S23[c] * w4.hi + (k4.hi * vv[c] - a4.hi * sa[c]);
;                     py[(t * 32 + 4 * c) * 4] = yp[c] + 0.25f * (vv[c] * sc.x - sa[c] * sc.y);
;                 }
;                 kk4 = nkk; wr4 = nwr; w4 = nw; k4 = nk; a4 = na; vv[0] = nv0; vv[1] = nv1; sc = nsc;
;             }
	v_mul_f32_e32 v83, v60, v62
	v_add_f32_dpp v81, v67, v66 quad_perm:[1,0,3,2] row_mask:0xf bank_mask:0xf bound_ctrl:1
	v_pk_fma_f32 v[6:7], v[58:59], v[76:77], v[72:73] op_sel_hi:[0,1,1] neg_lo:[1,0,0] neg_hi:[1,0,0]
	v_pk_fma_f32 v[8:9], v[58:59], v[76:77], v[74:75] op_sel:[1,0,0] op_sel_hi:[1,1,1] neg_lo:[1,0,0] neg_hi:[1,0,0]
	v_add_f32_dpp v82, v81, v81 quad_perm:[3,2,1,0] row_mask:0xf bank_mask:0xf bound_ctrl:1
	v_fma_f32 v83, -v76, v63, v83
	v_fmac_f32_e32 v82, 0x3e800000, v83
	ds_write_b32 v14, v82 offset:3584
	s_waitcnt lgkmcnt(7)
	v_pk_mul_f32 v[64:65], v[2:3], v[16:17] op_sel_hi:[1,0]
	v_pk_mul_f32 v[66:67], v[2:3], v[20:21] op_sel_hi:[1,0]
	ds_read_b128 v[40:43], v10 offset:2304
	v_pk_fma_f32 v[64:65], v[4:5], v[16:17], v[64:65] op_sel:[0,1,0] op_sel_hi:[1,1,1]
	v_pk_fma_f32 v[66:67], v[4:5], v[20:21], v[66:67] op_sel:[0,1,0] op_sel_hi:[1,1,1]
	ds_read_b128 v[44:47], v10 offset:10496
	v_pk_fma_f32 v[64:65], v[6:7], v[18:19], v[64:65] op_sel_hi:[1,0,1]
	v_pk_fma_f32 v[66:67], v[6:7], v[22:23], v[66:67] op_sel_hi:[1,0,1]
	ds_read_b128 v[48:51], v10 offset:18688
	v_pk_fma_f32 v[64:65], v[8:9], v[18:19], v[64:65] op_sel:[0,1,0] op_sel_hi:[1,1,1]
	v_pk_fma_f32 v[66:67], v[8:9], v[22:23], v[66:67] op_sel:[0,1,0] op_sel_hi:[1,1,1]
	ds_read_b128 v[52:55], v10 offset:26880
	v_add_f32_dpp v78, v65, v64 quad_perm:[1,0,3,2] row_mask:0xf bank_mask:0xf bound_ctrl:1
	ds_read_b128 v[56:59], v10 offset:35072
	ds_read_b32 v60, v11 offset:42112
	v_add_f32_dpp v79, v78, v78 quad_perm:[3,2,1,0] row_mask:0xf bank_mask:0xf bound_ctrl:1
	ds_read_b32 v61, v12 offset:42112
	ds_read_b64 v[62:63], v13 offset:45128
	v_add_f32_dpp v80, v79, v79 row_half_mirror row_mask:0xf bank_mask:0xf bound_ctrl:1
	s_waitcnt lgkmcnt(10)
	v_pk_mul_f32 v[68:69], v[36:37], v[28:29] op_sel_hi:[1,0]
	v_add_f32_dpp v76, v80, v80 row_mirror row_mask:0xf bank_mask:0xf bound_ctrl:1
	v_pk_mul_f32 v[70:71], v[36:37], v[28:29] op_sel:[0,1] op_sel_hi:[1,1]
	v_pk_mul_f32 v[72:73], v[36:37], v[30:31] op_sel_hi:[1,0]
	v_mov_b32_dpp v77, v76 quad_perm:[1,0,3,2] row_mask:0xf bank_mask:0xf bound_ctrl:1
	v_pk_mul_f32 v[74:75], v[36:37], v[30:31] op_sel:[0,1] op_sel_hi:[1,1]
	v_pk_fma_f32 v[68:69], v[2:3], v[24:25], v[68:69] op_sel_hi:[1,0,1]
	v_pk_fma_f32 v[70:71], v[4:5], v[24:25], v[70:71] op_sel:[0,1,0] op_sel_hi:[1,1,1]
	v_pk_fma_f32 v[72:73], v[6:7], v[26:27], v[72:73] op_sel_hi:[1,0,1]
	v_pk_fma_f32 v[74:75], v[8:9], v[26:27], v[74:75] op_sel:[0,1,0] op_sel_hi:[1,1,1]
	v_pk_fma_f32 v[2:3], v[32:33], v[76:77], v[68:69] op_sel_hi:[0,1,1] neg_lo:[1,0,0] neg_hi:[1,0,0]
	v_pk_fma_f32 v[4:5], v[32:33], v[76:77], v[70:71] op_sel:[1,0,0] op_sel_hi:[1,1,1] neg_lo:[1,0,0] neg_hi:[1,0,0]
	s_waitcnt lgkmcnt(9)
	v_mul_f32_e32 v83, v36, v38
	v_add_f32_dpp v81, v67, v66 quad_perm:[1,0,3,2] row_mask:0xf bank_mask:0xf bound_ctrl:1
	v_pk_fma_f32 v[6:7], v[34:35], v[76:77], v[72:73] op_sel_hi:[0,1,1] neg_lo:[1,0,0] neg_hi:[1,0,0]
	v_pk_fma_f32 v[8:9], v[34:35], v[76:77], v[74:75] op_sel:[1,0,0] op_sel_hi:[1,1,1] neg_lo:[1,0,0] neg_hi:[1,0,0]
	v_add_f32_dpp v82, v81, v81 quad_perm:[3,2,1,0] row_mask:0xf bank_mask:0xf bound_ctrl:1
	v_fma_f32 v83, -v76, v39, v83
	v_fmac_f32_e32 v82, 0x3e800000, v83
	ds_write_b32 v14, v82 offset:4096
	s_waitcnt lgkmcnt(7)
	v_pk_mul_f32 v[64:65], v[2:3], v[40:41] op_sel_hi:[1,0]
	v_pk_mul_f32 v[66:67], v[2:3], v[44:45] op_sel_hi:[1,0]
	ds_read_b128 v[16:19], v10 offset:2560
	v_pk_fma_f32 v[64:65], v[4:5], v[40:41], v[64:65] op_sel:[0,1,0] op_sel_hi:[1,1,1]
	v_pk_fma_f32 v[66:67], v[4:5], v[44:45], v[66:67] op_sel:[0,1,0] op_sel_hi:[1,1,1]
	ds_read_b128 v[20:23], v10 offset:10752
	v_pk_fma_f32 v[64:65], v[6:7], v[42:43], v[64:65] op_sel_hi:[1,0,1]
	v_pk_fma_f32 v[66:67], v[6:7], v[46:47], v[66:67] op_sel_hi:[1,0,1]
	ds_read_b128 v[24:27], v10 offset:18944
	v_pk_fma_f32 v[64:65], v[8:9], v[42:43], v[64:65] op_sel:[0,1,0] op_sel_hi:[1,1,1]
	v_pk_fma_f32 v[66:67], v[8:9], v[46:47], v[66:67] op_sel:[0,1,0] op_sel_hi:[1,1,1]
	ds_read_b128 v[28:31], v10 offset:27136
	v_add_f32_dpp v78, v65, v64 quad_perm:[1,0,3,2] row_mask:0xf bank_mask:0xf bound_ctrl:1
	ds_read_b128 v[32:35], v10 offset:35328
	ds_read_b32 v36, v11 offset:42240
	v_add_f32_dpp v79, v78, v78 quad_perm:[3,2,1,0] row_mask:0xf bank_mask:0xf bound_ctrl:1
	ds_read_b32 v37, v12 offset:42240
	ds_read_b64 v[38:39], v13 offset:45136
	v_add_f32_dpp v80, v79, v79 row_half_mirror row_mask:0xf bank_mask:0xf bound_ctrl:1
	s_waitcnt lgkmcnt(10)
	v_pk_mul_f32 v[68:69], v[60:61], v[52:53] op_sel_hi:[1,0]
	v_add_f32_dpp v76, v80, v80 row_mirror row_mask:0xf bank_mask:0xf bound_ctrl:1
	v_pk_mul_f32 v[70:71], v[60:61], v[52:53] op_sel:[0,1] op_sel_hi:[1,1]
	v_pk_mul_f32 v[72:73], v[60:61], v[54:55] op_sel_hi:[1,0]
	v_mov_b32_dpp v77, v76 quad_perm:[1,0,3,2] row_mask:0xf bank_mask:0xf bound_ctrl:1
	v_pk_mul_f32 v[74:75], v[60:61], v[54:55] op_sel:[0,1] op_sel_hi:[1,1]
	v_pk_fma_f32 v[68:69], v[2:3], v[48:49], v[68:69] op_sel_hi:[1,0,1]
	v_pk_fma_f32 v[70:71], v[4:5], v[48:49], v[70:71] op_sel:[0,1,0] op_sel_hi:[1,1,1]
	v_pk_fma_f32 v[72:73], v[6:7], v[50:51], v[72:73] op_sel_hi:[1,0,1]
	v_pk_fma_f32 v[74:75], v[8:9], v[50:51], v[74:75] op_sel:[0,1,0] op_sel_hi:[1,1,1]
	v_pk_fma_f32 v[2:3], v[56:57], v[76:77], v[68:69] op_sel_hi:[0,1,1] neg_lo:[1,0,0] neg_hi:[1,0,0]
	v_pk_fma_f32 v[4:5], v[56:57], v[76:77], v[70:71] op_sel:[1,0,0] op_sel_hi:[1,1,1] neg_lo:[1,0,0] neg_hi:[1,0,0]
	s_waitcnt lgkmcnt(9)
; #define LAS __attribute__((address_space(3)))
; template <int CTRL> __device__ __forceinline__ float dppf(float x) { return __builtin_bit_cast(float, __builtin_amdgcn_mov_dpp(__builtin_bit_cast(int, x), CTRL, 0xf, 0xf, true)); }
; __device__ __forceinline__ float sum16(float x) { x = sum8(x); x += dppf<0x140>(x); return x; }
; __device__ __forceinline__ void rwkv_item(LAS unsigned char* lds, int l, const bf16_t* PROJ, const bf16_t* LO, bf16_t* YR, float* BON, int b, int h, int qv) {
;     ...
;             for (int t = 0; t < CH; ++t) {
;                 const int tn = (t + 1) & (CH - 1);
;                 const LAS float* pn = pk + tn * 64;
;                 const f32x4 nkk = *(const LAS f32x4*)(pn), nwr = *(const LAS f32x4*)(pn + 2048), nw = *(const LAS f32x4*)(pn + 4096), nk = *(const LAS f32x4*)(pn + 6144), na = *(const LAS f32x4*)(pn + 8192);
;                 const float nv0 = pv[tn * 32], nv1 = pv[tn * 32 + 4]; const f32x2 nsc = *(const LAS f32x2*)(ps + 2 * tn);
;                 float sa[2], yp[2];
; #pragma unroll
;                 for (int c = 0; c < 2; ++c) { const f32x2 pa = S23[c] * kk4.hi + S01[c] * kk4.lo, pb = S23[c] * wr4.hi + S01[c] * wr4.lo; sa[c] = pa.x + pa.y; yp[c] = pb.x + pb.y; }
; #pragma unroll
;                 for (int c = 0; c < 2; ++c) { sa[c] = sum16(sa[c]); yp[c] += dppf<0xB1>(yp[c]); yp[c] += dppf<0x4E>(yp[c]); }
; #pragma unroll
;                 for (int c = 0; c < 2; ++c) {
;                     S01[c] = S01[c] * w4.lo + (k4.lo * vv[c] - a4.lo * sa[c]);
;                     S23[c] = S23[c] * w4.hi + (k4.hi * vv[c] - a4.hi * sa[c]);
;                     py[(t * 32 + 4 * c) * 4] = yp[c] + 0.25f * (vv[c] * sc.x - sa[c] * sc.y);
;                 }
;                 kk4 = nkk; wr4 = nwr; w4 = nw; k4 = nk; a4 = na; vv[0] = nv0; vv[1] = nv1; sc = nsc;
;             }
	v_mul_f32_e32 v83, v60, v62
	v_add_f32_dpp v81, v67, v66 quad_perm:[1,0,3,2] row_mask:0xf bank_mask:0xf bound_ctrl:1
	v_pk_fma_f32 v[6:7], v[58:59], v[76:77], v[72:73] op_sel_hi:[0,1,1] neg_lo:[1,0,0] neg_hi:[1,0,0]
	v_pk_fma_f32 v[8:9], v[58:59], v[76:77], v[74:75] op_sel:[1,0,0] op_sel_hi:[1,1,1] neg_lo:[1,0,0] neg_hi:[1,0,0]
	v_add_f32_dpp v82, v81, v81 quad_perm:[3,2,1,0] row_mask:0xf bank_mask:0xf bound_ctrl:1
	v_fma_f32 v83, -v76, v63, v83
	v_fmac_f32_e32 v82, 0x3e800000, v83
	ds_write_b32 v14, v82 offset:4608
	s_waitcnt lgkmcnt(7)
	v_pk_mul_f32 v[64:65], v[2:3], v[16:17] op_sel_hi:[1,0]
	v_pk_mul_f32 v[66:67], v[2:3], v[20:21] op_sel_hi:[1,0]
	ds_read_b128 v[40:43], v10 offset:2816
	v_pk_fma_f32 v[64:65], v[4:5], v[16:17], v[64:65] op_sel:[0,1,0] op_sel_hi:[1,1,1]
	v_pk_fma_f32 v[66:67], v[4:5], v[20:21], v[66:67] op_sel:[0,1,0] op_sel_hi:[1,1,1]
	ds_read_b128 v[44:47], v10 offset:11008
	v_pk_fma_f32 v[64:65], v[6:7], v[18:19], v[64:65] op_sel_hi:[1,0,1]
	v_pk_fma_f32 v[66:67], v[6:7], v[22:23], v[66:67] op_sel_hi:[1,0,1]
	ds_read_b128 v[48:51], v10 offset:19200
	v_pk_fma_f32 v[64:65], v[8:9], v[18:19], v[64:65] op_sel:[0,1,0] op_sel_hi:[1,1,1]
	v_pk_fma_f32 v[66:67], v[8:9], v[22:23], v[66:67] op_sel:[0,1,0] op_sel_hi:[1,1,1]
	ds_read_b128 v[52:55], v10 offset:27392
	v_add_f32_dpp v78, v65, v64 quad_perm:[1,0,3,2] row_mask:0xf bank_mask:0xf bound_ctrl:1
	ds_read_b128 v[56:59], v10 offset:35584
	ds_read_b32 v60, v11 offset:42368
	v_add_f32_dpp v79, v78, v78 quad_perm:[3,2,1,0] row_mask:0xf bank_mask:0xf bound_ctrl:1
	ds_read_b32 v61, v12 offset:42368
	ds_read_b64 v[62:63], v13 offset:45144
	v_add_f32_dpp v80, v79, v79 row_half_mirror row_mask:0xf bank_mask:0xf bound_ctrl:1
	s_waitcnt lgkmcnt(10)
	v_pk_mul_f32 v[68:69], v[36:37], v[28:29] op_sel_hi:[1,0]
	v_add_f32_dpp v76, v80, v80 row_mirror row_mask:0xf bank_mask:0xf bound_ctrl:1
	v_pk_mul_f32 v[70:71], v[36:37], v[28:29] op_sel:[0,1] op_sel_hi:[1,1]
	v_pk_mul_f32 v[72:73], v[36:37], v[30:31] op_sel_hi:[1,0]
	v_mov_b32_dpp v77, v76 quad_perm:[1,0,3,2] row_mask:0xf bank_mask:0xf bound_ctrl:1
	v_pk_mul_f32 v[74:75], v[36:37], v[30:31] op_sel:[0,1] op_sel_hi:[1,1]
	v_pk_fma_f32 v[68:69], v[2:3], v[24:25], v[68:69] op_sel_hi:[1,0,1]
	v_pk_fma_f32 v[70:71], v[4:5], v[24:25], v[70:71] op_sel:[0,1,0] op_sel_hi:[1,1,1]
	v_pk_fma_f32 v[72:73], v[6:7], v[26:27], v[72:73] op_sel_hi:[1,0,1]
	v_pk_fma_f32 v[74:75], v[8:9], v[26:27], v[74:75] op_sel:[0,1,0] op_sel_hi:[1,1,1]
	v_pk_fma_f32 v[2:3], v[32:33], v[76:77], v[68:69] op_sel_hi:[0,1,1] neg_lo:[1,0,0] neg_hi:[1,0,0]
	v_pk_fma_f32 v[4:5], v[32:33], v[76:77], v[70:71] op_sel:[1,0,0] op_sel_hi:[1,1,1] neg_lo:[1,0,0] neg_hi:[1,0,0]
	s_waitcnt lgkmcnt(9)
	v_mul_f32_e32 v83, v36, v38
	v_add_f32_dpp v81, v67, v66 quad_perm:[1,0,3,2] row_mask:0xf bank_mask:0xf bound_ctrl:1
	v_pk_fma_f32 v[6:7], v[34:35], v[76:77], v[72:73] op_sel_hi:[0,1,1] neg_lo:[1,0,0] neg_hi:[1,0,0]
	v_pk_fma_f32 v[8:9], v[34:35], v[76:77], v[74:75] op_sel:[1,0,0] op_sel_hi:[1,1,1] neg_lo:[1,0,0] neg_hi:[1,0,0]
	v_add_f32_dpp v82, v81, v81 quad_perm:[3,2,1,0] row_mask:0xf bank_mask:0xf bound_ctrl:1
	v_fma_f32 v83, -v76, v39, v83
	v_fmac_f32_e32 v82, 0x3e800000, v83
	ds_write_b32 v14, v82 offset:5120
	s_waitcnt lgkmcnt(7)
	v_pk_mul_f32 v[64:65], v[2:3], v[40:41] op_sel_hi:[1,0]
	v_pk_mul_f32 v[66:67], v[2:3], v[44:45] op_sel_hi:[1,0]
	ds_read_b128 v[16:19], v10 offset:3072
	v_pk_fma_f32 v[64:65], v[4:5], v[40:41], v[64:65] op_sel:[0,1,0] op_sel_hi:[1,1,1]
	v_pk_fma_f32 v[66:67], v[4:5], v[44:45], v[66:67] op_sel:[0,1,0] op_sel_hi:[1,1,1]
	ds_read_b128 v[20:23], v10 offset:11264
	v_pk_fma_f32 v[64:65], v[6:7], v[42:43], v[64:65] op_sel_hi:[1,0,1]
	v_pk_fma_f32 v[66:67], v[6:7], v[46:47], v[66:67] op_sel_hi:[1,0,1]
	ds_read_b128 v[24:27], v10 offset:19456
	v_pk_fma_f32 v[64:65], v[8:9], v[42:43], v[64:65] op_sel:[0,1,0] op_sel_hi:[1,1,1]
	v_pk_fma_f32 v[66:67], v[8:9], v[46:47], v[66:67] op_sel:[0,1,0] op_sel_hi:[1,1,1]
	ds_read_b128 v[28:31], v10 offset:27648
	v_add_f32_dpp v78, v65, v64 quad_perm:[1,0,3,2] row_mask:0xf bank_mask:0xf bound_ctrl:1
	ds_read_b128 v[32:35], v10 offset:35840
	ds_read_b32 v36, v11 offset:42496
	v_add_f32_dpp v79, v78, v78 quad_perm:[3,2,1,0] row_mask:0xf bank_mask:0xf bound_ctrl:1
	ds_read_b32 v37, v12 offset:42496
	ds_read_b64 v[38:39], v13 offset:45152
	v_add_f32_dpp v80, v79, v79 row_half_mirror row_mask:0xf bank_mask:0xf bound_ctrl:1
	s_waitcnt lgkmcnt(10)
	v_pk_mul_f32 v[68:69], v[60:61], v[52:53] op_sel_hi:[1,0]
	v_add_f32_dpp v76, v80, v80 row_mirror row_mask:0xf bank_mask:0xf bound_ctrl:1
	v_pk_mul_f32 v[70:71], v[60:61], v[52:53] op_sel:[0,1] op_sel_hi:[1,1]
	v_pk_mul_f32 v[72:73], v[60:61], v[54:55] op_sel_hi:[1,0]
	v_mov_b32_dpp v77, v76 quad_perm:[1,0,3,2] row_mask:0xf bank_mask:0xf bound_ctrl:1
	v_pk_mul_f32 v[74:75], v[60:61], v[54:55] op_sel:[0,1] op_sel_hi:[1,1]
	v_pk_fma_f32 v[68:69], v[2:3], v[48:49], v[68:69] op_sel_hi:[1,0,1]
	v_pk_fma_f32 v[70:71], v[4:5], v[48:49], v[70:71] op_sel:[0,1,0] op_sel_hi:[1,1,1]
	v_pk_fma_f32 v[72:73], v[6:7], v[50:51], v[72:73] op_sel_hi:[1,0,1]
	v_pk_fma_f32 v[74:75], v[8:9], v[50:51], v[74:75] op_sel:[0,1,0] op_sel_hi:[1,1,1]
	v_pk_fma_f32 v[2:3], v[56:57], v[76:77], v[68:69] op_sel_hi:[0,1,1] neg_lo:[1,0,0] neg_hi:[1,0,0]
	v_pk_fma_f32 v[4:5], v[56:57], v[76:77], v[70:71] op_sel:[1,0,0] op_sel_hi:[1,1,1] neg_lo:[1,0,0] neg_hi:[1,0,0]
	s_waitcnt lgkmcnt(9)
; #define LAS __attribute__((address_space(3)))
; template <int CTRL> __device__ __forceinline__ float dppf(float x) { return __builtin_bit_cast(float, __builtin_amdgcn_mov_dpp(__builtin_bit_cast(int, x), CTRL, 0xf, 0xf, true)); }
; __device__ __forceinline__ float sum16(float x) { x = sum8(x); x += dppf<0x140>(x); return x; }
; __device__ __forceinline__ void rwkv_item(LAS unsigned char* lds, int l, const bf16_t* PROJ, const bf16_t* LO, bf16_t* YR, float* BON, int b, int h, int qv) {
;     ...
;             for (int t = 0; t < CH; ++t) {
;                 const int tn = (t + 1) & (CH - 1);
;                 const LAS float* pn = pk + tn * 64;
;                 const f32x4 nkk = *(const LAS f32x4*)(pn), nwr = *(const LAS f32x4*)(pn + 2048), nw = *(const LAS f32x4*)(pn + 4096), nk = *(const LAS f32x4*)(pn + 6144), na = *(const LAS f32x4*)(pn + 8192);
;                 const float nv0 = pv[tn * 32], nv1 = pv[tn * 32 + 4]; const f32x2 nsc = *(const LAS f32x2*)(ps + 2 * tn);
;                 float sa[2], yp[2];
; #pragma unroll
;                 for (int c = 0; c < 2; ++c) { const f32x2 pa = S23[c] * kk4.hi + S01[c] * kk4.lo, pb = S23[c] * wr4.hi + S01[c] * wr4.lo; sa[c] = pa.x + pa.y; yp[c] = pb.x + pb.y; }
; #pragma unroll
;                 for (int c = 0; c < 2; ++c) { sa[c] = sum16(sa[c]); yp[c] += dppf<0xB1>(yp[c]); yp[c] += dppf<0x4E>(yp[c]); }
; #pragma unroll
;                 for (int c = 0; c < 2; ++c) {
;                     S01[c] = S01[c] * w4.lo + (k4.lo * vv[c] - a4.lo * sa[c]);
;                     S23[c] = S23[c] * w4.hi + (k4.hi * vv[c] - a4.hi * sa[c]);
;                     py[(t * 32 + 4 * c) * 4] = yp[c] + 0.25f * (vv[c] * sc.x - sa[c] * sc.y);
;                 }
;                 kk4 = nkk; wr4 = nwr; w4 = nw; k4 = nk; a4 = na; vv[0] = nv0; vv[1] = nv1; sc = nsc;
;             }
	v_mul_f32_e32 v83, v60, v62
	v_add_f32_dpp v81, v67, v66 quad_perm:[1,0,3,2] row_mask:0xf bank_mask:0xf bound_ctrl:1
	v_pk_fma_f32 v[6:7], v[58:59], v[76:77], v[72:73] op_sel_hi:[0,1,1] neg_lo:[1,0,0] neg_hi:[1,0,0]
	v_pk_fma_f32 v[8:9], v[58:59], v[76:77], v[74:75] op_sel:[1,0,0] op_sel_hi:[1,1,1] neg_lo:[1,0,0] neg_hi:[1,0,0]
	v_add_f32_dpp v82, v81, v81 quad_perm:[3,2,1,0] row_mask:0xf bank_mask:0xf bound_ctrl:1
	v_fma_f32 v83, -v76, v63, v83
	v_fmac_f32_e32 v82, 0x3e800000, v83
	ds_write_b32 v14, v82 offset:5632
	s_waitcnt lgkmcnt(7)
	v_pk_mul_f32 v[64:65], v[2:3], v[16:17] op_sel_hi:[1,0]
	v_pk_mul_f32 v[66:67], v[2:3], v[20:21] op_sel_hi:[1,0]
	ds_read_b128 v[40:43], v10 offset:3328
	v_pk_fma_f32 v[64:65], v[4:5], v[16:17], v[64:65] op_sel:[0,1,0] op_sel_hi:[1,1,1]
	v_pk_fma_f32 v[66:67], v[4:5], v[20:21], v[66:67] op_sel:[0,1,0] op_sel_hi:[1,1,1]
	ds_read_b128 v[44:47], v10 offset:11520
	v_pk_fma_f32 v[64:65], v[6:7], v[18:19], v[64:65] op_sel_hi:[1,0,1]
	v_pk_fma_f32 v[66:67], v[6:7], v[22:23], v[66:67] op_sel_hi:[1,0,1]
	ds_read_b128 v[48:51], v10 offset:19712
	v_pk_fma_f32 v[64:65], v[8:9], v[18:19], v[64:65] op_sel:[0,1,0] op_sel_hi:[1,1,1]
	v_pk_fma_f32 v[66:67], v[8:9], v[22:23], v[66:67] op_sel:[0,1,0] op_sel_hi:[1,1,1]
	ds_read_b128 v[52:55], v10 offset:27904
	v_add_f32_dpp v78, v65, v64 quad_perm:[1,0,3,2] row_mask:0xf bank_mask:0xf bound_ctrl:1
	ds_read_b128 v[56:59], v10 offset:36096
	ds_read_b32 v60, v11 offset:42624
	v_add_f32_dpp v79, v78, v78 quad_perm:[3,2,1,0] row_mask:0xf bank_mask:0xf bound_ctrl:1
	ds_read_b32 v61, v12 offset:42624
	ds_read_b64 v[62:63], v13 offset:45160
	v_add_f32_dpp v80, v79, v79 row_half_mirror row_mask:0xf bank_mask:0xf bound_ctrl:1
	s_waitcnt lgkmcnt(10)
	v_pk_mul_f32 v[68:69], v[36:37], v[28:29] op_sel_hi:[1,0]
	v_add_f32_dpp v76, v80, v80 row_mirror row_mask:0xf bank_mask:0xf bound_ctrl:1
	v_pk_mul_f32 v[70:71], v[36:37], v[28:29] op_sel:[0,1] op_sel_hi:[1,1]
	v_pk_mul_f32 v[72:73], v[36:37], v[30:31] op_sel_hi:[1,0]
	v_mov_b32_dpp v77, v76 quad_perm:[1,0,3,2] row_mask:0xf bank_mask:0xf bound_ctrl:1
	v_pk_mul_f32 v[74:75], v[36:37], v[30:31] op_sel:[0,1] op_sel_hi:[1,1]
	v_pk_fma_f32 v[68:69], v[2:3], v[24:25], v[68:69] op_sel_hi:[1,0,1]
	v_pk_fma_f32 v[70:71], v[4:5], v[24:25], v[70:71] op_sel:[0,1,0] op_sel_hi:[1,1,1]
	v_pk_fma_f32 v[72:73], v[6:7], v[26:27], v[72:73] op_sel_hi:[1,0,1]
	v_pk_fma_f32 v[74:75], v[8:9], v[26:27], v[74:75] op_sel:[0,1,0] op_sel_hi:[1,1,1]
	v_pk_fma_f32 v[2:3], v[32:33], v[76:77], v[68:69] op_sel_hi:[0,1,1] neg_lo:[1,0,0] neg_hi:[1,0,0]
	v_pk_fma_f32 v[4:5], v[32:33], v[76:77], v[70:71] op_sel:[1,0,0] op_sel_hi:[1,1,1] neg_lo:[1,0,0] neg_hi:[1,0,0]
	s_waitcnt lgkmcnt(9)
	v_mul_f32_e32 v83, v36, v38
	v_add_f32_dpp v81, v67, v66 quad_perm:[1,0,3,2] row_mask:0xf bank_mask:0xf bound_ctrl:1
	v_pk_fma_f32 v[6:7], v[34:35], v[76:77], v[72:73] op_sel_hi:[0,1,1] neg_lo:[1,0,0] neg_hi:[1,0,0]
	v_pk_fma_f32 v[8:9], v[34:35], v[76:77], v[74:75] op_sel:[1,0,0] op_sel_hi:[1,1,1] neg_lo:[1,0,0] neg_hi:[1,0,0]
	v_add_f32_dpp v82, v81, v81 quad_perm:[3,2,1,0] row_mask:0xf bank_mask:0xf bound_ctrl:1
	v_fma_f32 v83, -v76, v39, v83
	v_fmac_f32_e32 v82, 0x3e800000, v83
	ds_write_b32 v14, v82 offset:6144
	s_waitcnt lgkmcnt(7)
	v_pk_mul_f32 v[64:65], v[2:3], v[40:41] op_sel_hi:[1,0]
	v_pk_mul_f32 v[66:67], v[2:3], v[44:45] op_sel_hi:[1,0]
	ds_read_b128 v[16:19], v10 offset:3584
	v_pk_fma_f32 v[64:65], v[4:5], v[40:41], v[64:65] op_sel:[0,1,0] op_sel_hi:[1,1,1]
	v_pk_fma_f32 v[66:67], v[4:5], v[44:45], v[66:67] op_sel:[0,1,0] op_sel_hi:[1,1,1]
	ds_read_b128 v[20:23], v10 offset:11776
	v_pk_fma_f32 v[64:65], v[6:7], v[42:43], v[64:65] op_sel_hi:[1,0,1]
	v_pk_fma_f32 v[66:67], v[6:7], v[46:47], v[66:67] op_sel_hi:[1,0,1]
	ds_read_b128 v[24:27], v10 offset:19968
	v_pk_fma_f32 v[64:65], v[8:9], v[42:43], v[64:65] op_sel:[0,1,0] op_sel_hi:[1,1,1]
	v_pk_fma_f32 v[66:67], v[8:9], v[46:47], v[66:67] op_sel:[0,1,0] op_sel_hi:[1,1,1]
	ds_read_b128 v[28:31], v10 offset:28160
	v_add_f32_dpp v78, v65, v64 quad_perm:[1,0,3,2] row_mask:0xf bank_mask:0xf bound_ctrl:1
	ds_read_b128 v[32:35], v10 offset:36352
	ds_read_b32 v36, v11 offset:42752
	v_add_f32_dpp v79, v78, v78 quad_perm:[3,2,1,0] row_mask:0xf bank_mask:0xf bound_ctrl:1
	ds_read_b32 v37, v12 offset:42752
	ds_read_b64 v[38:39], v13 offset:45168
	v_add_f32_dpp v80, v79, v79 row_half_mirror row_mask:0xf bank_mask:0xf bound_ctrl:1
	s_waitcnt lgkmcnt(10)
	v_pk_mul_f32 v[68:69], v[60:61], v[52:53] op_sel_hi:[1,0]
	v_add_f32_dpp v76, v80, v80 row_mirror row_mask:0xf bank_mask:0xf bound_ctrl:1
	v_pk_mul_f32 v[70:71], v[60:61], v[52:53] op_sel:[0,1] op_sel_hi:[1,1]
	v_pk_mul_f32 v[72:73], v[60:61], v[54:55] op_sel_hi:[1,0]
	v_mov_b32_dpp v77, v76 quad_perm:[1,0,3,2] row_mask:0xf bank_mask:0xf bound_ctrl:1
	v_pk_mul_f32 v[74:75], v[60:61], v[54:55] op_sel:[0,1] op_sel_hi:[1,1]
	v_pk_fma_f32 v[68:69], v[2:3], v[48:49], v[68:69] op_sel_hi:[1,0,1]
	v_pk_fma_f32 v[70:71], v[4:5], v[48:49], v[70:71] op_sel:[0,1,0] op_sel_hi:[1,1,1]
	v_pk_fma_f32 v[72:73], v[6:7], v[50:51], v[72:73] op_sel_hi:[1,0,1]
	v_pk_fma_f32 v[74:75], v[8:9], v[50:51], v[74:75] op_sel:[0,1,0] op_sel_hi:[1,1,1]
	v_pk_fma_f32 v[2:3], v[56:57], v[76:77], v[68:69] op_sel_hi:[0,1,1] neg_lo:[1,0,0] neg_hi:[1,0,0]
	v_pk_fma_f32 v[4:5], v[56:57], v[76:77], v[70:71] op_sel:[1,0,0] op_sel_hi:[1,1,1] neg_lo:[1,0,0] neg_hi:[1,0,0]
	s_waitcnt lgkmcnt(9)
; #define LAS __attribute__((address_space(3)))
; template <int CTRL> __device__ __forceinline__ float dppf(float x) { return __builtin_bit_cast(float, __builtin_amdgcn_mov_dpp(__builtin_bit_cast(int, x), CTRL, 0xf, 0xf, true)); }
; __device__ __forceinline__ float sum16(float x) { x = sum8(x); x += dppf<0x140>(x); return x; }
; __device__ __forceinline__ void rwkv_item(LAS unsigned char* lds, int l, const bf16_t* PROJ, const bf16_t* LO, bf16_t* YR, float* BON, int b, int h, int qv) {
;     ...
;             for (int t = 0; t < CH; ++t) {
;                 const int tn = (t + 1) & (CH - 1);
;                 const LAS float* pn = pk + tn * 64;
;                 const f32x4 nkk = *(const LAS f32x4*)(pn), nwr = *(const LAS f32x4*)(pn + 2048), nw = *(const LAS f32x4*)(pn + 4096), nk = *(const LAS f32x4*)(pn + 6144), na = *(const LAS f32x4*)(pn + 8192);
;                 const float nv0 = pv[tn * 32], nv1 = pv[tn * 32 + 4]; const f32x2 nsc = *(const LAS f32x2*)(ps + 2 * tn);
;                 float sa[2], yp[2];
; #pragma unroll
;                 for (int c = 0; c < 2; ++c) { const f32x2 pa = S23[c] * kk4.hi + S01[c] * kk4.lo, pb = S23[c] * wr4.hi + S01[c] * wr4.lo; sa[c] = pa.x + pa.y; yp[c] = pb.x + pb.y; }
; #pragma unroll
;                 for (int c = 0; c < 2; ++c) { sa[c] = sum16(sa[c]); yp[c] += dppf<0xB1>(yp[c]); yp[c] += dppf<0x4E>(yp[c]); }
; #pragma unroll
;                 for (int c = 0; c < 2; ++c) {
;                     S01[c] = S01[c] * w4.lo + (k4.lo * vv[c] - a4.lo * sa[c]);
;                     S23[c] = S23[c] * w4.hi + (k4.hi * vv[c] - a4.hi * sa[c]);
;                     py[(t * 32 + 4 * c) * 4] = yp[c] + 0.25f * (vv[c] * sc.x - sa[c] * sc.y);
;                 }
;                 kk4 = nkk; wr4 = nwr; w4 = nw; k4 = nk; a4 = na; vv[0] = nv0; vv[1] = nv1; sc = nsc;
;             }
	v_mul_f32_e32 v83, v60, v62
	v_add_f32_dpp v81, v67, v66 quad_perm:[1,0,3,2] row_mask:0xf bank_mask:0xf bound_ctrl:1
	v_pk_fma_f32 v[6:7], v[58:59], v[76:77], v[72:73] op_sel_hi:[0,1,1] neg_lo:[1,0,0] neg_hi:[1,0,0]
	v_pk_fma_f32 v[8:9], v[58:59], v[76:77], v[74:75] op_sel:[1,0,0] op_sel_hi:[1,1,1] neg_lo:[1,0,0] neg_hi:[1,0,0]
	v_add_f32_dpp v82, v81, v81 quad_perm:[3,2,1,0] row_mask:0xf bank_mask:0xf bound_ctrl:1
	v_fma_f32 v83, -v76, v63, v83
	v_fmac_f32_e32 v82, 0x3e800000, v83
	ds_write_b32 v14, v82 offset:6656
	s_waitcnt lgkmcnt(7)
	v_pk_mul_f32 v[64:65], v[2:3], v[16:17] op_sel_hi:[1,0]
	v_pk_mul_f32 v[66:67], v[2:3], v[20:21] op_sel_hi:[1,0]
	ds_read_b128 v[40:43], v10 offset:3840
	v_pk_fma_f32 v[64:65], v[4:5], v[16:17], v[64:65] op_sel:[0,1,0] op_sel_hi:[1,1,1]
	v_pk_fma_f32 v[66:67], v[4:5], v[20:21], v[66:67] op_sel:[0,1,0] op_sel_hi:[1,1,1]
	ds_read_b128 v[44:47], v10 offset:12032
	v_pk_fma_f32 v[64:65], v[6:7], v[18:19], v[64:65] op_sel_hi:[1,0,1]
	v_pk_fma_f32 v[66:67], v[6:7], v[22:23], v[66:67] op_sel_hi:[1,0,1]
	ds_read_b128 v[48:51], v10 offset:20224
	v_pk_fma_f32 v[64:65], v[8:9], v[18:19], v[64:65] op_sel:[0,1,0] op_sel_hi:[1,1,1]
	v_pk_fma_f32 v[66:67], v[8:9], v[22:23], v[66:67] op_sel:[0,1,0] op_sel_hi:[1,1,1]
	ds_read_b128 v[52:55], v10 offset:28416
	v_add_f32_dpp v78, v65, v64 quad_perm:[1,0,3,2] row_mask:0xf bank_mask:0xf bound_ctrl:1
	ds_read_b128 v[56:59], v10 offset:36608
	ds_read_b32 v60, v11 offset:42880
	v_add_f32_dpp v79, v78, v78 quad_perm:[3,2,1,0] row_mask:0xf bank_mask:0xf bound_ctrl:1
	ds_read_b32 v61, v12 offset:42880
	ds_read_b64 v[62:63], v13 offset:45176
	v_add_f32_dpp v80, v79, v79 row_half_mirror row_mask:0xf bank_mask:0xf bound_ctrl:1
	s_waitcnt lgkmcnt(10)
	v_pk_mul_f32 v[68:69], v[36:37], v[28:29] op_sel_hi:[1,0]
	v_add_f32_dpp v76, v80, v80 row_mirror row_mask:0xf bank_mask:0xf bound_ctrl:1
	v_pk_mul_f32 v[70:71], v[36:37], v[28:29] op_sel:[0,1] op_sel_hi:[1,1]
	v_pk_mul_f32 v[72:73], v[36:37], v[30:31] op_sel_hi:[1,0]
	v_mov_b32_dpp v77, v76 quad_perm:[1,0,3,2] row_mask:0xf bank_mask:0xf bound_ctrl:1
	v_pk_mul_f32 v[74:75], v[36:37], v[30:31] op_sel:[0,1] op_sel_hi:[1,1]
	v_pk_fma_f32 v[68:69], v[2:3], v[24:25], v[68:69] op_sel_hi:[1,0,1]
	v_pk_fma_f32 v[70:71], v[4:5], v[24:25], v[70:71] op_sel:[0,1,0] op_sel_hi:[1,1,1]
	v_pk_fma_f32 v[72:73], v[6:7], v[26:27], v[72:73] op_sel_hi:[1,0,1]
	v_pk_fma_f32 v[74:75], v[8:9], v[26:27], v[74:75] op_sel:[0,1,0] op_sel_hi:[1,1,1]
	v_pk_fma_f32 v[2:3], v[32:33], v[76:77], v[68:69] op_sel_hi:[0,1,1] neg_lo:[1,0,0] neg_hi:[1,0,0]
	v_pk_fma_f32 v[4:5], v[32:33], v[76:77], v[70:71] op_sel:[1,0,0] op_sel_hi:[1,1,1] neg_lo:[1,0,0] neg_hi:[1,0,0]
	s_waitcnt lgkmcnt(9)
	v_mul_f32_e32 v83, v36, v38
	v_add_f32_dpp v81, v67, v66 quad_perm:[1,0,3,2] row_mask:0xf bank_mask:0xf bound_ctrl:1
	v_pk_fma_f32 v[6:7], v[34:35], v[76:77], v[72:73] op_sel_hi:[0,1,1] neg_lo:[1,0,0] neg_hi:[1,0,0]
	v_pk_fma_f32 v[8:9], v[34:35], v[76:77], v[74:75] op_sel:[1,0,0] op_sel_hi:[1,1,1] neg_lo:[1,0,0] neg_hi:[1,0,0]
	v_add_f32_dpp v82, v81, v81 quad_perm:[3,2,1,0] row_mask:0xf bank_mask:0xf bound_ctrl:1
	v_fma_f32 v83, -v76, v39, v83
	v_fmac_f32_e32 v82, 0x3e800000, v83
	ds_write_b32 v14, v82 offset:7168
	s_waitcnt lgkmcnt(7)
	v_pk_mul_f32 v[64:65], v[2:3], v[40:41] op_sel_hi:[1,0]
	v_pk_mul_f32 v[66:67], v[2:3], v[44:45] op_sel_hi:[1,0]
	ds_read_b128 v[16:19], v10 offset:4096
	v_pk_fma_f32 v[64:65], v[4:5], v[40:41], v[64:65] op_sel:[0,1,0] op_sel_hi:[1,1,1]
	v_pk_fma_f32 v[66:67], v[4:5], v[44:45], v[66:67] op_sel:[0,1,0] op_sel_hi:[1,1,1]
	ds_read_b128 v[20:23], v10 offset:12288
	v_pk_fma_f32 v[64:65], v[6:7], v[42:43], v[64:65] op_sel_hi:[1,0,1]
	v_pk_fma_f32 v[66:67], v[6:7], v[46:47], v[66:67] op_sel_hi:[1,0,1]
	ds_read_b128 v[24:27], v10 offset:20480
	v_pk_fma_f32 v[64:65], v[8:9], v[42:43], v[64:65] op_sel:[0,1,0] op_sel_hi:[1,1,1]
	v_pk_fma_f32 v[66:67], v[8:9], v[46:47], v[66:67] op_sel:[0,1,0] op_sel_hi:[1,1,1]
	ds_read_b128 v[28:31], v10 offset:28672
	v_add_f32_dpp v78, v65, v64 quad_perm:[1,0,3,2] row_mask:0xf bank_mask:0xf bound_ctrl:1
	ds_read_b128 v[32:35], v10 offset:36864
	ds_read_b32 v36, v11 offset:43008
	v_add_f32_dpp v79, v78, v78 quad_perm:[3,2,1,0] row_mask:0xf bank_mask:0xf bound_ctrl:1
	ds_read_b32 v37, v12 offset:43008
	ds_read_b64 v[38:39], v13 offset:45184
	v_add_f32_dpp v80, v79, v79 row_half_mirror row_mask:0xf bank_mask:0xf bound_ctrl:1
	s_waitcnt lgkmcnt(10)
	v_pk_mul_f32 v[68:69], v[60:61], v[52:53] op_sel_hi:[1,0]
	v_add_f32_dpp v76, v80, v80 row_mirror row_mask:0xf bank_mask:0xf bound_ctrl:1
	v_pk_mul_f32 v[70:71], v[60:61], v[52:53] op_sel:[0,1] op_sel_hi:[1,1]
	v_pk_mul_f32 v[72:73], v[60:61], v[54:55] op_sel_hi:[1,0]
	v_mov_b32_dpp v77, v76 quad_perm:[1,0,3,2] row_mask:0xf bank_mask:0xf bound_ctrl:1
	v_pk_mul_f32 v[74:75], v[60:61], v[54:55] op_sel:[0,1] op_sel_hi:[1,1]
	v_pk_fma_f32 v[68:69], v[2:3], v[48:49], v[68:69] op_sel_hi:[1,0,1]
	v_pk_fma_f32 v[70:71], v[4:5], v[48:49], v[70:71] op_sel:[0,1,0] op_sel_hi:[1,1,1]
	v_pk_fma_f32 v[72:73], v[6:7], v[50:51], v[72:73] op_sel_hi:[1,0,1]
	v_pk_fma_f32 v[74:75], v[8:9], v[50:51], v[74:75] op_sel:[0,1,0] op_sel_hi:[1,1,1]
	v_pk_fma_f32 v[2:3], v[56:57], v[76:77], v[68:69] op_sel_hi:[0,1,1] neg_lo:[1,0,0] neg_hi:[1,0,0]
	v_pk_fma_f32 v[4:5], v[56:57], v[76:77], v[70:71] op_sel:[1,0,0] op_sel_hi:[1,1,1] neg_lo:[1,0,0] neg_hi:[1,0,0]
	s_waitcnt lgkmcnt(9)
; #define LAS __attribute__((address_space(3)))
; template <int CTRL> __device__ __forceinline__ float dppf(float x) { return __builtin_bit_cast(float, __builtin_amdgcn_mov_dpp(__builtin_bit_cast(int, x), CTRL, 0xf, 0xf, true)); }
; __device__ __forceinline__ float sum16(float x) { x = sum8(x); x += dppf<0x140>(x); return x; }
; __device__ __forceinline__ void rwkv_item(LAS unsigned char* lds, int l, const bf16_t* PROJ, const bf16_t* LO, bf16_t* YR, float* BON, int b, int h, int qv) {
;     ...
;             for (int t = 0; t < CH; ++t) {
;                 const int tn = (t + 1) & (CH - 1);
;                 const LAS float* pn = pk + tn * 64;
;                 const f32x4 nkk = *(const LAS f32x4*)(pn), nwr = *(const LAS f32x4*)(pn + 2048), nw = *(const LAS f32x4*)(pn + 4096), nk = *(const LAS f32x4*)(pn + 6144), na = *(const LAS f32x4*)(pn + 8192);
;                 const float nv0 = pv[tn * 32], nv1 = pv[tn * 32 + 4]; const f32x2 nsc = *(const LAS f32x2*)(ps + 2 * tn);
;                 float sa[2], yp[2];
; #pragma unroll
;                 for (int c = 0; c < 2; ++c) { const f32x2 pa = S23[c] * kk4.hi + S01[c] * kk4.lo, pb = S23[c] * wr4.hi + S01[c] * wr4.lo; sa[c] = pa.x + pa.y; yp[c] = pb.x + pb.y; }
; #pragma unroll
;                 for (int c = 0; c < 2; ++c) { sa[c] = sum16(sa[c]); yp[c] += dppf<0xB1>(yp[c]); yp[c] += dppf<0x4E>(yp[c]); }
; #pragma unroll
;                 for (int c = 0; c < 2; ++c) {
;                     S01[c] = S01[c] * w4.lo + (k4.lo * vv[c] - a4.lo * sa[c]);
;                     S23[c] = S23[c] * w4.hi + (k4.hi * vv[c] - a4.hi * sa[c]);
;                     py[(t * 32 + 4 * c) * 4] = yp[c] + 0.25f * (vv[c] * sc.x - sa[c] * sc.y);
;                 }
;                 kk4 = nkk; wr4 = nwr; w4 = nw; k4 = nk; a4 = na; vv[0] = nv0; vv[1] = nv1; sc = nsc;
;             }
	v_mul_f32_e32 v83, v60, v62
	v_add_f32_dpp v81, v67, v66 quad_perm:[1,0,3,2] row_mask:0xf bank_mask:0xf bound_ctrl:1
	v_pk_fma_f32 v[6:7], v[58:59], v[76:77], v[72:73] op_sel_hi:[0,1,1] neg_lo:[1,0,0] neg_hi:[1,0,0]
	v_pk_fma_f32 v[8:9], v[58:59], v[76:77], v[74:75] op_sel:[1,0,0] op_sel_hi:[1,1,1] neg_lo:[1,0,0] neg_hi:[1,0,0]
	v_add_f32_dpp v82, v81, v81 quad_perm:[3,2,1,0] row_mask:0xf bank_mask:0xf bound_ctrl:1
	v_fma_f32 v83, -v76, v63, v83
	v_fmac_f32_e32 v82, 0x3e800000, v83
	ds_write_b32 v14, v82 offset:7680
	s_waitcnt lgkmcnt(7)
	v_pk_mul_f32 v[64:65], v[2:3], v[16:17] op_sel_hi:[1,0]
	v_pk_mul_f32 v[66:67], v[2:3], v[20:21] op_sel_hi:[1,0]
	ds_read_b128 v[40:43], v10 offset:4352
	v_pk_fma_f32 v[64:65], v[4:5], v[16:17], v[64:65] op_sel:[0,1,0] op_sel_hi:[1,1,1]
	v_pk_fma_f32 v[66:67], v[4:5], v[20:21], v[66:67] op_sel:[0,1,0] op_sel_hi:[1,1,1]
	ds_read_b128 v[44:47], v10 offset:12544
	v_pk_fma_f32 v[64:65], v[6:7], v[18:19], v[64:65] op_sel_hi:[1,0,1]
	v_pk_fma_f32 v[66:67], v[6:7], v[22:23], v[66:67] op_sel_hi:[1,0,1]
	ds_read_b128 v[48:51], v10 offset:20736
	v_pk_fma_f32 v[64:65], v[8:9], v[18:19], v[64:65] op_sel:[0,1,0] op_sel_hi:[1,1,1]
	v_pk_fma_f32 v[66:67], v[8:9], v[22:23], v[66:67] op_sel:[0,1,0] op_sel_hi:[1,1,1]
	ds_read_b128 v[52:55], v10 offset:28928
	v_add_f32_dpp v78, v65, v64 quad_perm:[1,0,3,2] row_mask:0xf bank_mask:0xf bound_ctrl:1
	ds_read_b128 v[56:59], v10 offset:37120
	ds_read_b32 v60, v11 offset:43136
	v_add_f32_dpp v79, v78, v78 quad_perm:[3,2,1,0] row_mask:0xf bank_mask:0xf bound_ctrl:1
	ds_read_b32 v61, v12 offset:43136
	ds_read_b64 v[62:63], v13 offset:45192
	v_add_f32_dpp v80, v79, v79 row_half_mirror row_mask:0xf bank_mask:0xf bound_ctrl:1
	s_waitcnt lgkmcnt(10)
	v_pk_mul_f32 v[68:69], v[36:37], v[28:29] op_sel_hi:[1,0]
	v_add_f32_dpp v76, v80, v80 row_mirror row_mask:0xf bank_mask:0xf bound_ctrl:1
	v_pk_mul_f32 v[70:71], v[36:37], v[28:29] op_sel:[0,1] op_sel_hi:[1,1]
	v_pk_mul_f32 v[72:73], v[36:37], v[30:31] op_sel_hi:[1,0]
	v_mov_b32_dpp v77, v76 quad_perm:[1,0,3,2] row_mask:0xf bank_mask:0xf bound_ctrl:1
	v_pk_mul_f32 v[74:75], v[36:37], v[30:31] op_sel:[0,1] op_sel_hi:[1,1]
	v_pk_fma_f32 v[68:69], v[2:3], v[24:25], v[68:69] op_sel_hi:[1,0,1]
	v_pk_fma_f32 v[70:71], v[4:5], v[24:25], v[70:71] op_sel:[0,1,0] op_sel_hi:[1,1,1]
	v_pk_fma_f32 v[72:73], v[6:7], v[26:27], v[72:73] op_sel_hi:[1,0,1]
	v_pk_fma_f32 v[74:75], v[8:9], v[26:27], v[74:75] op_sel:[0,1,0] op_sel_hi:[1,1,1]
	v_pk_fma_f32 v[2:3], v[32:33], v[76:77], v[68:69] op_sel_hi:[0,1,1] neg_lo:[1,0,0] neg_hi:[1,0,0]
	v_pk_fma_f32 v[4:5], v[32:33], v[76:77], v[70:71] op_sel:[1,0,0] op_sel_hi:[1,1,1] neg_lo:[1,0,0] neg_hi:[1,0,0]
	s_waitcnt lgkmcnt(9)
	v_mul_f32_e32 v83, v36, v38
	v_add_f32_dpp v81, v67, v66 quad_perm:[1,0,3,2] row_mask:0xf bank_mask:0xf bound_ctrl:1
	v_pk_fma_f32 v[6:7], v[34:35], v[76:77], v[72:73] op_sel_hi:[0,1,1] neg_lo:[1,0,0] neg_hi:[1,0,0]
	v_pk_fma_f32 v[8:9], v[34:35], v[76:77], v[74:75] op_sel:[1,0,0] op_sel_hi:[1,1,1] neg_lo:[1,0,0] neg_hi:[1,0,0]
	v_add_f32_dpp v82, v81, v81 quad_perm:[3,2,1,0] row_mask:0xf bank_mask:0xf bound_ctrl:1
	v_fma_f32 v83, -v76, v39, v83
	v_fmac_f32_e32 v82, 0x3e800000, v83
	ds_write_b32 v14, v82 offset:8192
	s_waitcnt lgkmcnt(7)
	v_pk_mul_f32 v[64:65], v[2:3], v[40:41] op_sel_hi:[1,0]
	v_pk_mul_f32 v[66:67], v[2:3], v[44:45] op_sel_hi:[1,0]
	ds_read_b128 v[16:19], v10 offset:4608
	v_pk_fma_f32 v[64:65], v[4:5], v[40:41], v[64:65] op_sel:[0,1,0] op_sel_hi:[1,1,1]
	v_pk_fma_f32 v[66:67], v[4:5], v[44:45], v[66:67] op_sel:[0,1,0] op_sel_hi:[1,1,1]
	ds_read_b128 v[20:23], v10 offset:12800
	v_pk_fma_f32 v[64:65], v[6:7], v[42:43], v[64:65] op_sel_hi:[1,0,1]
	v_pk_fma_f32 v[66:67], v[6:7], v[46:47], v[66:67] op_sel_hi:[1,0,1]
	ds_read_b128 v[24:27], v10 offset:20992
	v_pk_fma_f32 v[64:65], v[8:9], v[42:43], v[64:65] op_sel:[0,1,0] op_sel_hi:[1,1,1]
	v_pk_fma_f32 v[66:67], v[8:9], v[46:47], v[66:67] op_sel:[0,1,0] op_sel_hi:[1,1,1]
	ds_read_b128 v[28:31], v10 offset:29184
	v_add_f32_dpp v78, v65, v64 quad_perm:[1,0,3,2] row_mask:0xf bank_mask:0xf bound_ctrl:1
	ds_read_b128 v[32:35], v10 offset:37376
	ds_read_b32 v36, v11 offset:43264
	v_add_f32_dpp v79, v78, v78 quad_perm:[3,2,1,0] row_mask:0xf bank_mask:0xf bound_ctrl:1
	ds_read_b32 v37, v12 offset:43264
	ds_read_b64 v[38:39], v13 offset:45200
	v_add_f32_dpp v80, v79, v79 row_half_mirror row_mask:0xf bank_mask:0xf bound_ctrl:1
	s_waitcnt lgkmcnt(10)
	v_pk_mul_f32 v[68:69], v[60:61], v[52:53] op_sel_hi:[1,0]
	v_add_f32_dpp v76, v80, v80 row_mirror row_mask:0xf bank_mask:0xf bound_ctrl:1
	v_pk_mul_f32 v[70:71], v[60:61], v[52:53] op_sel:[0,1] op_sel_hi:[1,1]
	v_pk_mul_f32 v[72:73], v[60:61], v[54:55] op_sel_hi:[1,0]
	v_mov_b32_dpp v77, v76 quad_perm:[1,0,3,2] row_mask:0xf bank_mask:0xf bound_ctrl:1
	v_pk_mul_f32 v[74:75], v[60:61], v[54:55] op_sel:[0,1] op_sel_hi:[1,1]
	v_pk_fma_f32 v[68:69], v[2:3], v[48:49], v[68:69] op_sel_hi:[1,0,1]
	v_pk_fma_f32 v[70:71], v[4:5], v[48:49], v[70:71] op_sel:[0,1,0] op_sel_hi:[1,1,1]
	v_pk_fma_f32 v[72:73], v[6:7], v[50:51], v[72:73] op_sel_hi:[1,0,1]
	v_pk_fma_f32 v[74:75], v[8:9], v[50:51], v[74:75] op_sel:[0,1,0] op_sel_hi:[1,1,1]
	v_pk_fma_f32 v[2:3], v[56:57], v[76:77], v[68:69] op_sel_hi:[0,1,1] neg_lo:[1,0,0] neg_hi:[1,0,0]
	v_pk_fma_f32 v[4:5], v[56:57], v[76:77], v[70:71] op_sel:[1,0,0] op_sel_hi:[1,1,1] neg_lo:[1,0,0] neg_hi:[1,0,0]
	s_waitcnt lgkmcnt(9)
; #define LAS __attribute__((address_space(3)))
; template <int CTRL> __device__ __forceinline__ float dppf(float x) { return __builtin_bit_cast(float, __builtin_amdgcn_mov_dpp(__builtin_bit_cast(int, x), CTRL, 0xf, 0xf, true)); }
; __device__ __forceinline__ float sum16(float x) { x = sum8(x); x += dppf<0x140>(x); return x; }
; __device__ __forceinline__ void rwkv_item(LAS unsigned char* lds, int l, const bf16_t* PROJ, const bf16_t* LO, bf16_t* YR, float* BON, int b, int h, int qv) {
;     ...
;             for (int t = 0; t < CH; ++t) {
;                 const int tn = (t + 1) & (CH - 1);
;                 const LAS float* pn = pk + tn * 64;
;                 const f32x4 nkk = *(const LAS f32x4*)(pn), nwr = *(const LAS f32x4*)(pn + 2048), nw = *(const LAS f32x4*)(pn + 4096), nk = *(const LAS f32x4*)(pn + 6144), na = *(const LAS f32x4*)(pn + 8192);
;                 const float nv0 = pv[tn * 32], nv1 = pv[tn * 32 + 4]; const f32x2 nsc = *(const LAS f32x2*)(ps + 2 * tn);
;                 float sa[2], yp[2];
; #pragma unroll
;                 for (int c = 0; c < 2; ++c) { const f32x2 pa = S23[c] * kk4.hi + S01[c] * kk4.lo, pb = S23[c] * wr4.hi + S01[c] * wr4.lo; sa[c] = pa.x + pa.y; yp[c] = pb.x + pb.y; }
; #pragma unroll
;                 for (int c = 0; c < 2; ++c) { sa[c] = sum16(sa[c]); yp[c] += dppf<0xB1>(yp[c]); yp[c] += dppf<0x4E>(yp[c]); }
; #pragma unroll
;                 for (int c = 0; c < 2; ++c) {
;                     S01[c] = S01[c] * w4.lo + (k4.lo * vv[c] - a4.lo * sa[c]);
;                     S23[c] = S23[c] * w4.hi + (k4.hi * vv[c] - a4.hi * sa[c]);
;                     py[(t * 32 + 4 * c) * 4] = yp[c] + 0.25f * (vv[c] * sc.x - sa[c] * sc.y);
;                 }
;                 kk4 = nkk; wr4 = nwr; w4 = nw; k4 = nk; a4 = na; vv[0] = nv0; vv[1] = nv1; sc = nsc;
;             }
	v_mul_f32_e32 v83, v60, v62
	v_add_f32_dpp v81, v67, v66 quad_perm:[1,0,3,2] row_mask:0xf bank_mask:0xf bound_ctrl:1
	v_pk_fma_f32 v[6:7], v[58:59], v[76:77], v[72:73] op_sel_hi:[0,1,1] neg_lo:[1,0,0] neg_hi:[1,0,0]
	v_pk_fma_f32 v[8:9], v[58:59], v[76:77], v[74:75] op_sel:[1,0,0] op_sel_hi:[1,1,1] neg_lo:[1,0,0] neg_hi:[1,0,0]
	v_add_f32_dpp v82, v81, v81 quad_perm:[3,2,1,0] row_mask:0xf bank_mask:0xf bound_ctrl:1
	v_fma_f32 v83, -v76, v63, v83
	v_fmac_f32_e32 v82, 0x3e800000, v83
	ds_write_b32 v14, v82 offset:8704
	s_waitcnt lgkmcnt(7)
	v_pk_mul_f32 v[64:65], v[2:3], v[16:17] op_sel_hi:[1,0]
	v_pk_mul_f32 v[66:67], v[2:3], v[20:21] op_sel_hi:[1,0]
	ds_read_b128 v[40:43], v10 offset:4864
	v_pk_fma_f32 v[64:65], v[4:5], v[16:17], v[64:65] op_sel:[0,1,0] op_sel_hi:[1,1,1]
	v_pk_fma_f32 v[66:67], v[4:5], v[20:21], v[66:67] op_sel:[0,1,0] op_sel_hi:[1,1,1]
	ds_read_b128 v[44:47], v10 offset:13056
	v_pk_fma_f32 v[64:65], v[6:7], v[18:19], v[64:65] op_sel_hi:[1,0,1]
	v_pk_fma_f32 v[66:67], v[6:7], v[22:23], v[66:67] op_sel_hi:[1,0,1]
	ds_read_b128 v[48:51], v10 offset:21248
	v_pk_fma_f32 v[64:65], v[8:9], v[18:19], v[64:65] op_sel:[0,1,0] op_sel_hi:[1,1,1]
	v_pk_fma_f32 v[66:67], v[8:9], v[22:23], v[66:67] op_sel:[0,1,0] op_sel_hi:[1,1,1]
	ds_read_b128 v[52:55], v10 offset:29440
	v_add_f32_dpp v78, v65, v64 quad_perm:[1,0,3,2] row_mask:0xf bank_mask:0xf bound_ctrl:1
	ds_read_b128 v[56:59], v10 offset:37632
	ds_read_b32 v60, v11 offset:43392
	v_add_f32_dpp v79, v78, v78 quad_perm:[3,2,1,0] row_mask:0xf bank_mask:0xf bound_ctrl:1
	ds_read_b32 v61, v12 offset:43392
	ds_read_b64 v[62:63], v13 offset:45208
	v_add_f32_dpp v80, v79, v79 row_half_mirror row_mask:0xf bank_mask:0xf bound_ctrl:1
	s_waitcnt lgkmcnt(10)
	v_pk_mul_f32 v[68:69], v[36:37], v[28:29] op_sel_hi:[1,0]
	v_add_f32_dpp v76, v80, v80 row_mirror row_mask:0xf bank_mask:0xf bound_ctrl:1
	v_pk_mul_f32 v[70:71], v[36:37], v[28:29] op_sel:[0,1] op_sel_hi:[1,1]
	v_pk_mul_f32 v[72:73], v[36:37], v[30:31] op_sel_hi:[1,0]
	v_mov_b32_dpp v77, v76 quad_perm:[1,0,3,2] row_mask:0xf bank_mask:0xf bound_ctrl:1
	v_pk_mul_f32 v[74:75], v[36:37], v[30:31] op_sel:[0,1] op_sel_hi:[1,1]
	v_pk_fma_f32 v[68:69], v[2:3], v[24:25], v[68:69] op_sel_hi:[1,0,1]
	v_pk_fma_f32 v[70:71], v[4:5], v[24:25], v[70:71] op_sel:[0,1,0] op_sel_hi:[1,1,1]
	v_pk_fma_f32 v[72:73], v[6:7], v[26:27], v[72:73] op_sel_hi:[1,0,1]
	v_pk_fma_f32 v[74:75], v[8:9], v[26:27], v[74:75] op_sel:[0,1,0] op_sel_hi:[1,1,1]
	v_pk_fma_f32 v[2:3], v[32:33], v[76:77], v[68:69] op_sel_hi:[0,1,1] neg_lo:[1,0,0] neg_hi:[1,0,0]
	v_pk_fma_f32 v[4:5], v[32:33], v[76:77], v[70:71] op_sel:[1,0,0] op_sel_hi:[1,1,1] neg_lo:[1,0,0] neg_hi:[1,0,0]
	s_waitcnt lgkmcnt(9)
	v_mul_f32_e32 v83, v36, v38
	v_add_f32_dpp v81, v67, v66 quad_perm:[1,0,3,2] row_mask:0xf bank_mask:0xf bound_ctrl:1
	v_pk_fma_f32 v[6:7], v[34:35], v[76:77], v[72:73] op_sel_hi:[0,1,1] neg_lo:[1,0,0] neg_hi:[1,0,0]
	v_pk_fma_f32 v[8:9], v[34:35], v[76:77], v[74:75] op_sel:[1,0,0] op_sel_hi:[1,1,1] neg_lo:[1,0,0] neg_hi:[1,0,0]
	v_add_f32_dpp v82, v81, v81 quad_perm:[3,2,1,0] row_mask:0xf bank_mask:0xf bound_ctrl:1
	v_fma_f32 v83, -v76, v39, v83
	v_fmac_f32_e32 v82, 0x3e800000, v83
	ds_write_b32 v14, v82 offset:9216
	s_waitcnt lgkmcnt(7)
	v_pk_mul_f32 v[64:65], v[2:3], v[40:41] op_sel_hi:[1,0]
	v_pk_mul_f32 v[66:67], v[2:3], v[44:45] op_sel_hi:[1,0]
	ds_read_b128 v[16:19], v10 offset:5120
	v_pk_fma_f32 v[64:65], v[4:5], v[40:41], v[64:65] op_sel:[0,1,0] op_sel_hi:[1,1,1]
	v_pk_fma_f32 v[66:67], v[4:5], v[44:45], v[66:67] op_sel:[0,1,0] op_sel_hi:[1,1,1]
	ds_read_b128 v[20:23], v10 offset:13312
	v_pk_fma_f32 v[64:65], v[6:7], v[42:43], v[64:65] op_sel_hi:[1,0,1]
	v_pk_fma_f32 v[66:67], v[6:7], v[46:47], v[66:67] op_sel_hi:[1,0,1]
	ds_read_b128 v[24:27], v10 offset:21504
	v_pk_fma_f32 v[64:65], v[8:9], v[42:43], v[64:65] op_sel:[0,1,0] op_sel_hi:[1,1,1]
	v_pk_fma_f32 v[66:67], v[8:9], v[46:47], v[66:67] op_sel:[0,1,0] op_sel_hi:[1,1,1]
	ds_read_b128 v[28:31], v10 offset:29696
	v_add_f32_dpp v78, v65, v64 quad_perm:[1,0,3,2] row_mask:0xf bank_mask:0xf bound_ctrl:1
	ds_read_b128 v[32:35], v10 offset:37888
	ds_read_b32 v36, v11 offset:43520
	v_add_f32_dpp v79, v78, v78 quad_perm:[3,2,1,0] row_mask:0xf bank_mask:0xf bound_ctrl:1
	ds_read_b32 v37, v12 offset:43520
	ds_read_b64 v[38:39], v13 offset:45216
	v_add_f32_dpp v80, v79, v79 row_half_mirror row_mask:0xf bank_mask:0xf bound_ctrl:1
	s_waitcnt lgkmcnt(10)
	v_pk_mul_f32 v[68:69], v[60:61], v[52:53] op_sel_hi:[1,0]
	v_add_f32_dpp v76, v80, v80 row_mirror row_mask:0xf bank_mask:0xf bound_ctrl:1
	v_pk_mul_f32 v[70:71], v[60:61], v[52:53] op_sel:[0,1] op_sel_hi:[1,1]
	v_pk_mul_f32 v[72:73], v[60:61], v[54:55] op_sel_hi:[1,0]
	v_mov_b32_dpp v77, v76 quad_perm:[1,0,3,2] row_mask:0xf bank_mask:0xf bound_ctrl:1
	v_pk_mul_f32 v[74:75], v[60:61], v[54:55] op_sel:[0,1] op_sel_hi:[1,1]
	v_pk_fma_f32 v[68:69], v[2:3], v[48:49], v[68:69] op_sel_hi:[1,0,1]
	v_pk_fma_f32 v[70:71], v[4:5], v[48:49], v[70:71] op_sel:[0,1,0] op_sel_hi:[1,1,1]
	v_pk_fma_f32 v[72:73], v[6:7], v[50:51], v[72:73] op_sel_hi:[1,0,1]
	v_pk_fma_f32 v[74:75], v[8:9], v[50:51], v[74:75] op_sel:[0,1,0] op_sel_hi:[1,1,1]
	v_pk_fma_f32 v[2:3], v[56:57], v[76:77], v[68:69] op_sel_hi:[0,1,1] neg_lo:[1,0,0] neg_hi:[1,0,0]
	v_pk_fma_f32 v[4:5], v[56:57], v[76:77], v[70:71] op_sel:[1,0,0] op_sel_hi:[1,1,1] neg_lo:[1,0,0] neg_hi:[1,0,0]
	s_waitcnt lgkmcnt(9)
; #define LAS __attribute__((address_space(3)))
; template <int CTRL> __device__ __forceinline__ float dppf(float x) { return __builtin_bit_cast(float, __builtin_amdgcn_mov_dpp(__builtin_bit_cast(int, x), CTRL, 0xf, 0xf, true)); }
; __device__ __forceinline__ float sum16(float x) { x = sum8(x); x += dppf<0x140>(x); return x; }
; __device__ __forceinline__ void rwkv_item(LAS unsigned char* lds, int l, const bf16_t* PROJ, const bf16_t* LO, bf16_t* YR, float* BON, int b, int h, int qv) {
;     ...
;             for (int t = 0; t < CH; ++t) {
;                 const int tn = (t + 1) & (CH - 1);
;                 const LAS float* pn = pk + tn * 64;
;                 const f32x4 nkk = *(const LAS f32x4*)(pn), nwr = *(const LAS f32x4*)(pn + 2048), nw = *(const LAS f32x4*)(pn + 4096), nk = *(const LAS f32x4*)(pn + 6144), na = *(const LAS f32x4*)(pn + 8192);
;                 const float nv0 = pv[tn * 32], nv1 = pv[tn * 32 + 4]; const f32x2 nsc = *(const LAS f32x2*)(ps + 2 * tn);
;                 float sa[2], yp[2];
; #pragma unroll
;                 for (int c = 0; c < 2; ++c) { const f32x2 pa = S23[c] * kk4.hi + S01[c] * kk4.lo, pb = S23[c] * wr4.hi + S01[c] * wr4.lo; sa[c] = pa.x + pa.y; yp[c] = pb.x + pb.y; }
; #pragma unroll
;                 for (int c = 0; c < 2; ++c) { sa[c] = sum16(sa[c]); yp[c] += dppf<0xB1>(yp[c]); yp[c] += dppf<0x4E>(yp[c]); }
; #pragma unroll
;                 for (int c = 0; c < 2; ++c) {
;                     S01[c] = S01[c] * w4.lo + (k4.lo * vv[c] - a4.lo * sa[c]);
;                     S23[c] = S23[c] * w4.hi + (k4.hi * vv[c] - a4.hi * sa[c]);
;                     py[(t * 32 + 4 * c) * 4] = yp[c] + 0.25f * (vv[c] * sc.x - sa[c] * sc.y);
;                 }
;                 kk4 = nkk; wr4 = nwr; w4 = nw; k4 = nk; a4 = na; vv[0] = nv0; vv[1] = nv1; sc = nsc;
;             }
	v_mul_f32_e32 v83, v60, v62
	v_add_f32_dpp v81, v67, v66 quad_perm:[1,0,3,2] row_mask:0xf bank_mask:0xf bound_ctrl:1
	v_pk_fma_f32 v[6:7], v[58:59], v[76:77], v[72:73] op_sel_hi:[0,1,1] neg_lo:[1,0,0] neg_hi:[1,0,0]
	v_pk_fma_f32 v[8:9], v[58:59], v[76:77], v[74:75] op_sel:[1,0,0] op_sel_hi:[1,1,1] neg_lo:[1,0,0] neg_hi:[1,0,0]
	v_add_f32_dpp v82, v81, v81 quad_perm:[3,2,1,0] row_mask:0xf bank_mask:0xf bound_ctrl:1
	v_fma_f32 v83, -v76, v63, v83
	v_fmac_f32_e32 v82, 0x3e800000, v83
	ds_write_b32 v14, v82 offset:9728
	s_waitcnt lgkmcnt(7)
	v_pk_mul_f32 v[64:65], v[2:3], v[16:17] op_sel_hi:[1,0]
	v_pk_mul_f32 v[66:67], v[2:3], v[20:21] op_sel_hi:[1,0]
	ds_read_b128 v[40:43], v10 offset:5376
	v_pk_fma_f32 v[64:65], v[4:5], v[16:17], v[64:65] op_sel:[0,1,0] op_sel_hi:[1,1,1]
	v_pk_fma_f32 v[66:67], v[4:5], v[20:21], v[66:67] op_sel:[0,1,0] op_sel_hi:[1,1,1]
	ds_read_b128 v[44:47], v10 offset:13568
	v_pk_fma_f32 v[64:65], v[6:7], v[18:19], v[64:65] op_sel_hi:[1,0,1]
	v_pk_fma_f32 v[66:67], v[6:7], v[22:23], v[66:67] op_sel_hi:[1,0,1]
	ds_read_b128 v[48:51], v10 offset:21760
	v_pk_fma_f32 v[64:65], v[8:9], v[18:19], v[64:65] op_sel:[0,1,0] op_sel_hi:[1,1,1]
	v_pk_fma_f32 v[66:67], v[8:9], v[22:23], v[66:67] op_sel:[0,1,0] op_sel_hi:[1,1,1]
	ds_read_b128 v[52:55], v10 offset:29952
	v_add_f32_dpp v78, v65, v64 quad_perm:[1,0,3,2] row_mask:0xf bank_mask:0xf bound_ctrl:1
	ds_read_b128 v[56:59], v10 offset:38144
	ds_read_b32 v60, v11 offset:43648
	v_add_f32_dpp v79, v78, v78 quad_perm:[3,2,1,0] row_mask:0xf bank_mask:0xf bound_ctrl:1
	ds_read_b32 v61, v12 offset:43648
	ds_read_b64 v[62:63], v13 offset:45224
	v_add_f32_dpp v80, v79, v79 row_half_mirror row_mask:0xf bank_mask:0xf bound_ctrl:1
	s_waitcnt lgkmcnt(10)
	v_pk_mul_f32 v[68:69], v[36:37], v[28:29] op_sel_hi:[1,0]
	v_add_f32_dpp v76, v80, v80 row_mirror row_mask:0xf bank_mask:0xf bound_ctrl:1
	v_pk_mul_f32 v[70:71], v[36:37], v[28:29] op_sel:[0,1] op_sel_hi:[1,1]
	v_pk_mul_f32 v[72:73], v[36:37], v[30:31] op_sel_hi:[1,0]
	v_mov_b32_dpp v77, v76 quad_perm:[1,0,3,2] row_mask:0xf bank_mask:0xf bound_ctrl:1
	v_pk_mul_f32 v[74:75], v[36:37], v[30:31] op_sel:[0,1] op_sel_hi:[1,1]
	v_pk_fma_f32 v[68:69], v[2:3], v[24:25], v[68:69] op_sel_hi:[1,0,1]
	v_pk_fma_f32 v[70:71], v[4:5], v[24:25], v[70:71] op_sel:[0,1,0] op_sel_hi:[1,1,1]
	v_pk_fma_f32 v[72:73], v[6:7], v[26:27], v[72:73] op_sel_hi:[1,0,1]
	v_pk_fma_f32 v[74:75], v[8:9], v[26:27], v[74:75] op_sel:[0,1,0] op_sel_hi:[1,1,1]
	v_pk_fma_f32 v[2:3], v[32:33], v[76:77], v[68:69] op_sel_hi:[0,1,1] neg_lo:[1,0,0] neg_hi:[1,0,0]
	v_pk_fma_f32 v[4:5], v[32:33], v[76:77], v[70:71] op_sel:[1,0,0] op_sel_hi:[1,1,1] neg_lo:[1,0,0] neg_hi:[1,0,0]
	s_waitcnt lgkmcnt(9)
	v_mul_f32_e32 v83, v36, v38
	v_add_f32_dpp v81, v67, v66 quad_perm:[1,0,3,2] row_mask:0xf bank_mask:0xf bound_ctrl:1
	v_pk_fma_f32 v[6:7], v[34:35], v[76:77], v[72:73] op_sel_hi:[0,1,1] neg_lo:[1,0,0] neg_hi:[1,0,0]
	v_pk_fma_f32 v[8:9], v[34:35], v[76:77], v[74:75] op_sel:[1,0,0] op_sel_hi:[1,1,1] neg_lo:[1,0,0] neg_hi:[1,0,0]
	v_add_f32_dpp v82, v81, v81 quad_perm:[3,2,1,0] row_mask:0xf bank_mask:0xf bound_ctrl:1
	v_fma_f32 v83, -v76, v39, v83
	v_fmac_f32_e32 v82, 0x3e800000, v83
	ds_write_b32 v14, v82 offset:10240
	s_waitcnt lgkmcnt(7)
	v_pk_mul_f32 v[64:65], v[2:3], v[40:41] op_sel_hi:[1,0]
	v_pk_mul_f32 v[66:67], v[2:3], v[44:45] op_sel_hi:[1,0]
	ds_read_b128 v[16:19], v10 offset:5632
	v_pk_fma_f32 v[64:65], v[4:5], v[40:41], v[64:65] op_sel:[0,1,0] op_sel_hi:[1,1,1]
	v_pk_fma_f32 v[66:67], v[4:5], v[44:45], v[66:67] op_sel:[0,1,0] op_sel_hi:[1,1,1]
	ds_read_b128 v[20:23], v10 offset:13824
	v_pk_fma_f32 v[64:65], v[6:7], v[42:43], v[64:65] op_sel_hi:[1,0,1]
	v_pk_fma_f32 v[66:67], v[6:7], v[46:47], v[66:67] op_sel_hi:[1,0,1]
	ds_read_b128 v[24:27], v10 offset:22016
	v_pk_fma_f32 v[64:65], v[8:9], v[42:43], v[64:65] op_sel:[0,1,0] op_sel_hi:[1,1,1]
	v_pk_fma_f32 v[66:67], v[8:9], v[46:47], v[66:67] op_sel:[0,1,0] op_sel_hi:[1,1,1]
	ds_read_b128 v[28:31], v10 offset:30208
	v_add_f32_dpp v78, v65, v64 quad_perm:[1,0,3,2] row_mask:0xf bank_mask:0xf bound_ctrl:1
	ds_read_b128 v[32:35], v10 offset:38400
	ds_read_b32 v36, v11 offset:43776
	v_add_f32_dpp v79, v78, v78 quad_perm:[3,2,1,0] row_mask:0xf bank_mask:0xf bound_ctrl:1
	ds_read_b32 v37, v12 offset:43776
	ds_read_b64 v[38:39], v13 offset:45232
	v_add_f32_dpp v80, v79, v79 row_half_mirror row_mask:0xf bank_mask:0xf bound_ctrl:1
	s_waitcnt lgkmcnt(10)
	v_pk_mul_f32 v[68:69], v[60:61], v[52:53] op_sel_hi:[1,0]
	v_add_f32_dpp v76, v80, v80 row_mirror row_mask:0xf bank_mask:0xf bound_ctrl:1
	v_pk_mul_f32 v[70:71], v[60:61], v[52:53] op_sel:[0,1] op_sel_hi:[1,1]
	v_pk_mul_f32 v[72:73], v[60:61], v[54:55] op_sel_hi:[1,0]
	v_mov_b32_dpp v77, v76 quad_perm:[1,0,3,2] row_mask:0xf bank_mask:0xf bound_ctrl:1
	v_pk_mul_f32 v[74:75], v[60:61], v[54:55] op_sel:[0,1] op_sel_hi:[1,1]
	v_pk_fma_f32 v[68:69], v[2:3], v[48:49], v[68:69] op_sel_hi:[1,0,1]
	v_pk_fma_f32 v[70:71], v[4:5], v[48:49], v[70:71] op_sel:[0,1,0] op_sel_hi:[1,1,1]
	v_pk_fma_f32 v[72:73], v[6:7], v[50:51], v[72:73] op_sel_hi:[1,0,1]
	v_pk_fma_f32 v[74:75], v[8:9], v[50:51], v[74:75] op_sel:[0,1,0] op_sel_hi:[1,1,1]
	v_pk_fma_f32 v[2:3], v[56:57], v[76:77], v[68:69] op_sel_hi:[0,1,1] neg_lo:[1,0,0] neg_hi:[1,0,0]
	v_pk_fma_f32 v[4:5], v[56:57], v[76:77], v[70:71] op_sel:[1,0,0] op_sel_hi:[1,1,1] neg_lo:[1,0,0] neg_hi:[1,0,0]
	s_waitcnt lgkmcnt(9)
; #define LAS __attribute__((address_space(3)))
; template <int CTRL> __device__ __forceinline__ float dppf(float x) { return __builtin_bit_cast(float, __builtin_amdgcn_mov_dpp(__builtin_bit_cast(int, x), CTRL, 0xf, 0xf, true)); }
; __device__ __forceinline__ float sum16(float x) { x = sum8(x); x += dppf<0x140>(x); return x; }
; __device__ __forceinline__ void rwkv_item(LAS unsigned char* lds, int l, const bf16_t* PROJ, const bf16_t* LO, bf16_t* YR, float* BON, int b, int h, int qv) {
;     ...
;             for (int t = 0; t < CH; ++t) {
;                 const int tn = (t + 1) & (CH - 1);
;                 const LAS float* pn = pk + tn * 64;
;                 const f32x4 nkk = *(const LAS f32x4*)(pn), nwr = *(const LAS f32x4*)(pn + 2048), nw = *(const LAS f32x4*)(pn + 4096), nk = *(const LAS f32x4*)(pn + 6144), na = *(const LAS f32x4*)(pn + 8192);
;                 const float nv0 = pv[tn * 32], nv1 = pv[tn * 32 + 4]; const f32x2 nsc = *(const LAS f32x2*)(ps + 2 * tn);
;                 float sa[2], yp[2];
; #pragma unroll
;                 for (int c = 0; c < 2; ++c) { const f32x2 pa = S23[c] * kk4.hi + S01[c] * kk4.lo, pb = S23[c] * wr4.hi + S01[c] * wr4.lo; sa[c] = pa.x + pa.y; yp[c] = pb.x + pb.y; }
; #pragma unroll
;                 for (int c = 0; c < 2; ++c) { sa[c] = sum16(sa[c]); yp[c] += dppf<0xB1>(yp[c]); yp[c] += dppf<0x4E>(yp[c]); }
; #pragma unroll
;                 for (int c = 0; c < 2; ++c) {
;                     S01[c] = S01[c] * w4.lo + (k4.lo * vv[c] - a4.lo * sa[c]);
;                     S23[c] = S23[c] * w4.hi + (k4.hi * vv[c] - a4.hi * sa[c]);
;                     py[(t * 32 + 4 * c) * 4] = yp[c] + 0.25f * (vv[c] * sc.x - sa[c] * sc.y);
;                 }
;                 kk4 = nkk; wr4 = nwr; w4 = nw; k4 = nk; a4 = na; vv[0] = nv0; vv[1] = nv1; sc = nsc;
;             }
	v_mul_f32_e32 v83, v60, v62
	v_add_f32_dpp v81, v67, v66 quad_perm:[1,0,3,2] row_mask:0xf bank_mask:0xf bound_ctrl:1
	v_pk_fma_f32 v[6:7], v[58:59], v[76:77], v[72:73] op_sel_hi:[0,1,1] neg_lo:[1,0,0] neg_hi:[1,0,0]
	v_pk_fma_f32 v[8:9], v[58:59], v[76:77], v[74:75] op_sel:[1,0,0] op_sel_hi:[1,1,1] neg_lo:[1,0,0] neg_hi:[1,0,0]
	v_add_f32_dpp v82, v81, v81 quad_perm:[3,2,1,0] row_mask:0xf bank_mask:0xf bound_ctrl:1
	v_fma_f32 v83, -v76, v63, v83
	v_fmac_f32_e32 v82, 0x3e800000, v83
	ds_write_b32 v14, v82 offset:10752
	s_waitcnt lgkmcnt(7)
	v_pk_mul_f32 v[64:65], v[2:3], v[16:17] op_sel_hi:[1,0]
	v_pk_mul_f32 v[66:67], v[2:3], v[20:21] op_sel_hi:[1,0]
	ds_read_b128 v[40:43], v10 offset:5888
	v_pk_fma_f32 v[64:65], v[4:5], v[16:17], v[64:65] op_sel:[0,1,0] op_sel_hi:[1,1,1]
	v_pk_fma_f32 v[66:67], v[4:5], v[20:21], v[66:67] op_sel:[0,1,0] op_sel_hi:[1,1,1]
	ds_read_b128 v[44:47], v10 offset:14080
	v_pk_fma_f32 v[64:65], v[6:7], v[18:19], v[64:65] op_sel_hi:[1,0,1]
	v_pk_fma_f32 v[66:67], v[6:7], v[22:23], v[66:67] op_sel_hi:[1,0,1]
	ds_read_b128 v[48:51], v10 offset:22272
	v_pk_fma_f32 v[64:65], v[8:9], v[18:19], v[64:65] op_sel:[0,1,0] op_sel_hi:[1,1,1]
	v_pk_fma_f32 v[66:67], v[8:9], v[22:23], v[66:67] op_sel:[0,1,0] op_sel_hi:[1,1,1]
	ds_read_b128 v[52:55], v10 offset:30464
	v_add_f32_dpp v78, v65, v64 quad_perm:[1,0,3,2] row_mask:0xf bank_mask:0xf bound_ctrl:1
	ds_read_b128 v[56:59], v10 offset:38656
	ds_read_b32 v60, v11 offset:43904
	v_add_f32_dpp v79, v78, v78 quad_perm:[3,2,1,0] row_mask:0xf bank_mask:0xf bound_ctrl:1
	ds_read_b32 v61, v12 offset:43904
	ds_read_b64 v[62:63], v13 offset:45240
	v_add_f32_dpp v80, v79, v79 row_half_mirror row_mask:0xf bank_mask:0xf bound_ctrl:1
	s_waitcnt lgkmcnt(10)
	v_pk_mul_f32 v[68:69], v[36:37], v[28:29] op_sel_hi:[1,0]
	v_add_f32_dpp v76, v80, v80 row_mirror row_mask:0xf bank_mask:0xf bound_ctrl:1
	v_pk_mul_f32 v[70:71], v[36:37], v[28:29] op_sel:[0,1] op_sel_hi:[1,1]
	v_pk_mul_f32 v[72:73], v[36:37], v[30:31] op_sel_hi:[1,0]
	v_mov_b32_dpp v77, v76 quad_perm:[1,0,3,2] row_mask:0xf bank_mask:0xf bound_ctrl:1
	v_pk_mul_f32 v[74:75], v[36:37], v[30:31] op_sel:[0,1] op_sel_hi:[1,1]
	v_pk_fma_f32 v[68:69], v[2:3], v[24:25], v[68:69] op_sel_hi:[1,0,1]
	v_pk_fma_f32 v[70:71], v[4:5], v[24:25], v[70:71] op_sel:[0,1,0] op_sel_hi:[1,1,1]
	v_pk_fma_f32 v[72:73], v[6:7], v[26:27], v[72:73] op_sel_hi:[1,0,1]
	v_pk_fma_f32 v[74:75], v[8:9], v[26:27], v[74:75] op_sel:[0,1,0] op_sel_hi:[1,1,1]
	v_pk_fma_f32 v[2:3], v[32:33], v[76:77], v[68:69] op_sel_hi:[0,1,1] neg_lo:[1,0,0] neg_hi:[1,0,0]
	v_pk_fma_f32 v[4:5], v[32:33], v[76:77], v[70:71] op_sel:[1,0,0] op_sel_hi:[1,1,1] neg_lo:[1,0,0] neg_hi:[1,0,0]
	s_waitcnt lgkmcnt(9)
	v_mul_f32_e32 v83, v36, v38
	v_add_f32_dpp v81, v67, v66 quad_perm:[1,0,3,2] row_mask:0xf bank_mask:0xf bound_ctrl:1
	v_pk_fma_f32 v[6:7], v[34:35], v[76:77], v[72:73] op_sel_hi:[0,1,1] neg_lo:[1,0,0] neg_hi:[1,0,0]
	v_pk_fma_f32 v[8:9], v[34:35], v[76:77], v[74:75] op_sel:[1,0,0] op_sel_hi:[1,1,1] neg_lo:[1,0,0] neg_hi:[1,0,0]
	v_add_f32_dpp v82, v81, v81 quad_perm:[3,2,1,0] row_mask:0xf bank_mask:0xf bound_ctrl:1
	v_fma_f32 v83, -v76, v39, v83
	v_fmac_f32_e32 v82, 0x3e800000, v83
	ds_write_b32 v14, v82 offset:11264
	s_waitcnt lgkmcnt(7)
	v_pk_mul_f32 v[64:65], v[2:3], v[40:41] op_sel_hi:[1,0]
	v_pk_mul_f32 v[66:67], v[2:3], v[44:45] op_sel_hi:[1,0]
	ds_read_b128 v[16:19], v10 offset:6144
	v_pk_fma_f32 v[64:65], v[4:5], v[40:41], v[64:65] op_sel:[0,1,0] op_sel_hi:[1,1,1]
	v_pk_fma_f32 v[66:67], v[4:5], v[44:45], v[66:67] op_sel:[0,1,0] op_sel_hi:[1,1,1]
	ds_read_b128 v[20:23], v10 offset:14336
	v_pk_fma_f32 v[64:65], v[6:7], v[42:43], v[64:65] op_sel_hi:[1,0,1]
	v_pk_fma_f32 v[66:67], v[6:7], v[46:47], v[66:67] op_sel_hi:[1,0,1]
	ds_read_b128 v[24:27], v10 offset:22528
	v_pk_fma_f32 v[64:65], v[8:9], v[42:43], v[64:65] op_sel:[0,1,0] op_sel_hi:[1,1,1]
	v_pk_fma_f32 v[66:67], v[8:9], v[46:47], v[66:67] op_sel:[0,1,0] op_sel_hi:[1,1,1]
	ds_read_b128 v[28:31], v10 offset:30720
	v_add_f32_dpp v78, v65, v64 quad_perm:[1,0,3,2] row_mask:0xf bank_mask:0xf bound_ctrl:1
	ds_read_b128 v[32:35], v10 offset:38912
	ds_read_b32 v36, v11 offset:44032
	v_add_f32_dpp v79, v78, v78 quad_perm:[3,2,1,0] row_mask:0xf bank_mask:0xf bound_ctrl:1
	ds_read_b32 v37, v12 offset:44032
	ds_read_b64 v[38:39], v13 offset:45248
	v_add_f32_dpp v80, v79, v79 row_half_mirror row_mask:0xf bank_mask:0xf bound_ctrl:1
	s_waitcnt lgkmcnt(10)
	v_pk_mul_f32 v[68:69], v[60:61], v[52:53] op_sel_hi:[1,0]
	v_add_f32_dpp v76, v80, v80 row_mirror row_mask:0xf bank_mask:0xf bound_ctrl:1
	v_pk_mul_f32 v[70:71], v[60:61], v[52:53] op_sel:[0,1] op_sel_hi:[1,1]
	v_pk_mul_f32 v[72:73], v[60:61], v[54:55] op_sel_hi:[1,0]
	v_mov_b32_dpp v77, v76 quad_perm:[1,0,3,2] row_mask:0xf bank_mask:0xf bound_ctrl:1
	v_pk_mul_f32 v[74:75], v[60:61], v[54:55] op_sel:[0,1] op_sel_hi:[1,1]
	v_pk_fma_f32 v[68:69], v[2:3], v[48:49], v[68:69] op_sel_hi:[1,0,1]
	v_pk_fma_f32 v[70:71], v[4:5], v[48:49], v[70:71] op_sel:[0,1,0] op_sel_hi:[1,1,1]
	v_pk_fma_f32 v[72:73], v[6:7], v[50:51], v[72:73] op_sel_hi:[1,0,1]
	v_pk_fma_f32 v[74:75], v[8:9], v[50:51], v[74:75] op_sel:[0,1,0] op_sel_hi:[1,1,1]
	v_pk_fma_f32 v[2:3], v[56:57], v[76:77], v[68:69] op_sel_hi:[0,1,1] neg_lo:[1,0,0] neg_hi:[1,0,0]
	v_pk_fma_f32 v[4:5], v[56:57], v[76:77], v[70:71] op_sel:[1,0,0] op_sel_hi:[1,1,1] neg_lo:[1,0,0] neg_hi:[1,0,0]
	s_waitcnt lgkmcnt(9)
; #define LAS __attribute__((address_space(3)))
; template <int CTRL> __device__ __forceinline__ float dppf(float x) { return __builtin_bit_cast(float, __builtin_amdgcn_mov_dpp(__builtin_bit_cast(int, x), CTRL, 0xf, 0xf, true)); }
; __device__ __forceinline__ float sum16(float x) { x = sum8(x); x += dppf<0x140>(x); return x; }
; __device__ __forceinline__ void rwkv_item(LAS unsigned char* lds, int l, const bf16_t* PROJ, const bf16_t* LO, bf16_t* YR, float* BON, int b, int h, int qv) {
;     ...
;             for (int t = 0; t < CH; ++t) {
;                 const int tn = (t + 1) & (CH - 1);
;                 const LAS float* pn = pk + tn * 64;
;                 const f32x4 nkk = *(const LAS f32x4*)(pn), nwr = *(const LAS f32x4*)(pn + 2048), nw = *(const LAS f32x4*)(pn + 4096), nk = *(const LAS f32x4*)(pn + 6144), na = *(const LAS f32x4*)(pn + 8192);
;                 const float nv0 = pv[tn * 32], nv1 = pv[tn * 32 + 4]; const f32x2 nsc = *(const LAS f32x2*)(ps + 2 * tn);
;                 float sa[2], yp[2];
; #pragma unroll
;                 for (int c = 0; c < 2; ++c) { const f32x2 pa = S23[c] * kk4.hi + S01[c] * kk4.lo, pb = S23[c] * wr4.hi + S01[c] * wr4.lo; sa[c] = pa.x + pa.y; yp[c] = pb.x + pb.y; }
; #pragma unroll
;                 for (int c = 0; c < 2; ++c) { sa[c] = sum16(sa[c]); yp[c] += dppf<0xB1>(yp[c]); yp[c] += dppf<0x4E>(yp[c]); }
; #pragma unroll
;                 for (int c = 0; c < 2; ++c) {
;                     S01[c] = S01[c] * w4.lo + (k4.lo * vv[c] - a4.lo * sa[c]);
;                     S23[c] = S23[c] * w4.hi + (k4.hi * vv[c] - a4.hi * sa[c]);
;                     py[(t * 32 + 4 * c) * 4] = yp[c] + 0.25f * (vv[c] * sc.x - sa[c] * sc.y);
;                 }
;                 kk4 = nkk; wr4 = nwr; w4 = nw; k4 = nk; a4 = na; vv[0] = nv0; vv[1] = nv1; sc = nsc;
;             }
	v_mul_f32_e32 v83, v60, v62
	v_add_f32_dpp v81, v67, v66 quad_perm:[1,0,3,2] row_mask:0xf bank_mask:0xf bound_ctrl:1
	v_pk_fma_f32 v[6:7], v[58:59], v[76:77], v[72:73] op_sel_hi:[0,1,1] neg_lo:[1,0,0] neg_hi:[1,0,0]
	v_pk_fma_f32 v[8:9], v[58:59], v[76:77], v[74:75] op_sel:[1,0,0] op_sel_hi:[1,1,1] neg_lo:[1,0,0] neg_hi:[1,0,0]
	v_add_f32_dpp v82, v81, v81 quad_perm:[3,2,1,0] row_mask:0xf bank_mask:0xf bound_ctrl:1
	v_fma_f32 v83, -v76, v63, v83
	v_fmac_f32_e32 v82, 0x3e800000, v83
	ds_write_b32 v14, v82 offset:11776
	s_waitcnt lgkmcnt(7)
	v_pk_mul_f32 v[64:65], v[2:3], v[16:17] op_sel_hi:[1,0]
	v_pk_mul_f32 v[66:67], v[2:3], v[20:21] op_sel_hi:[1,0]
	ds_read_b128 v[40:43], v10 offset:6400
	v_pk_fma_f32 v[64:65], v[4:5], v[16:17], v[64:65] op_sel:[0,1,0] op_sel_hi:[1,1,1]
	v_pk_fma_f32 v[66:67], v[4:5], v[20:21], v[66:67] op_sel:[0,1,0] op_sel_hi:[1,1,1]
	ds_read_b128 v[44:47], v10 offset:14592
	v_pk_fma_f32 v[64:65], v[6:7], v[18:19], v[64:65] op_sel_hi:[1,0,1]
	v_pk_fma_f32 v[66:67], v[6:7], v[22:23], v[66:67] op_sel_hi:[1,0,1]
	ds_read_b128 v[48:51], v10 offset:22784
	v_pk_fma_f32 v[64:65], v[8:9], v[18:19], v[64:65] op_sel:[0,1,0] op_sel_hi:[1,1,1]
	v_pk_fma_f32 v[66:67], v[8:9], v[22:23], v[66:67] op_sel:[0,1,0] op_sel_hi:[1,1,1]
	ds_read_b128 v[52:55], v10 offset:30976
	v_add_f32_dpp v78, v65, v64 quad_perm:[1,0,3,2] row_mask:0xf bank_mask:0xf bound_ctrl:1
	ds_read_b128 v[56:59], v10 offset:39168
	ds_read_b32 v60, v11 offset:44160
	v_add_f32_dpp v79, v78, v78 quad_perm:[3,2,1,0] row_mask:0xf bank_mask:0xf bound_ctrl:1
	ds_read_b32 v61, v12 offset:44160
	ds_read_b64 v[62:63], v13 offset:45256
	v_add_f32_dpp v80, v79, v79 row_half_mirror row_mask:0xf bank_mask:0xf bound_ctrl:1
	s_waitcnt lgkmcnt(10)
	v_pk_mul_f32 v[68:69], v[36:37], v[28:29] op_sel_hi:[1,0]
	v_add_f32_dpp v76, v80, v80 row_mirror row_mask:0xf bank_mask:0xf bound_ctrl:1
	v_pk_mul_f32 v[70:71], v[36:37], v[28:29] op_sel:[0,1] op_sel_hi:[1,1]
	v_pk_mul_f32 v[72:73], v[36:37], v[30:31] op_sel_hi:[1,0]
	v_mov_b32_dpp v77, v76 quad_perm:[1,0,3,2] row_mask:0xf bank_mask:0xf bound_ctrl:1
	v_pk_mul_f32 v[74:75], v[36:37], v[30:31] op_sel:[0,1] op_sel_hi:[1,1]
	v_pk_fma_f32 v[68:69], v[2:3], v[24:25], v[68:69] op_sel_hi:[1,0,1]
	v_pk_fma_f32 v[70:71], v[4:5], v[24:25], v[70:71] op_sel:[0,1,0] op_sel_hi:[1,1,1]
	v_pk_fma_f32 v[72:73], v[6:7], v[26:27], v[72:73] op_sel_hi:[1,0,1]
	v_pk_fma_f32 v[74:75], v[8:9], v[26:27], v[74:75] op_sel:[0,1,0] op_sel_hi:[1,1,1]
	v_pk_fma_f32 v[2:3], v[32:33], v[76:77], v[68:69] op_sel_hi:[0,1,1] neg_lo:[1,0,0] neg_hi:[1,0,0]
	v_pk_fma_f32 v[4:5], v[32:33], v[76:77], v[70:71] op_sel:[1,0,0] op_sel_hi:[1,1,1] neg_lo:[1,0,0] neg_hi:[1,0,0]
	s_waitcnt lgkmcnt(9)
	v_mul_f32_e32 v83, v36, v38
	v_add_f32_dpp v81, v67, v66 quad_perm:[1,0,3,2] row_mask:0xf bank_mask:0xf bound_ctrl:1
	v_pk_fma_f32 v[6:7], v[34:35], v[76:77], v[72:73] op_sel_hi:[0,1,1] neg_lo:[1,0,0] neg_hi:[1,0,0]
	v_pk_fma_f32 v[8:9], v[34:35], v[76:77], v[74:75] op_sel:[1,0,0] op_sel_hi:[1,1,1] neg_lo:[1,0,0] neg_hi:[1,0,0]
	v_add_f32_dpp v82, v81, v81 quad_perm:[3,2,1,0] row_mask:0xf bank_mask:0xf bound_ctrl:1
	v_fma_f32 v83, -v76, v39, v83
	v_fmac_f32_e32 v82, 0x3e800000, v83
	ds_write_b32 v14, v82 offset:12288
	s_waitcnt lgkmcnt(7)
	v_pk_mul_f32 v[64:65], v[2:3], v[40:41] op_sel_hi:[1,0]
	v_pk_mul_f32 v[66:67], v[2:3], v[44:45] op_sel_hi:[1,0]
	ds_read_b128 v[16:19], v10 offset:6656
	v_pk_fma_f32 v[64:65], v[4:5], v[40:41], v[64:65] op_sel:[0,1,0] op_sel_hi:[1,1,1]
	v_pk_fma_f32 v[66:67], v[4:5], v[44:45], v[66:67] op_sel:[0,1,0] op_sel_hi:[1,1,1]
	ds_read_b128 v[20:23], v10 offset:14848
	v_pk_fma_f32 v[64:65], v[6:7], v[42:43], v[64:65] op_sel_hi:[1,0,1]
	v_pk_fma_f32 v[66:67], v[6:7], v[46:47], v[66:67] op_sel_hi:[1,0,1]
	ds_read_b128 v[24:27], v10 offset:23040
	v_pk_fma_f32 v[64:65], v[8:9], v[42:43], v[64:65] op_sel:[0,1,0] op_sel_hi:[1,1,1]
	v_pk_fma_f32 v[66:67], v[8:9], v[46:47], v[66:67] op_sel:[0,1,0] op_sel_hi:[1,1,1]
	ds_read_b128 v[28:31], v10 offset:31232
	v_add_f32_dpp v78, v65, v64 quad_perm:[1,0,3,2] row_mask:0xf bank_mask:0xf bound_ctrl:1
	ds_read_b128 v[32:35], v10 offset:39424
	ds_read_b32 v36, v11 offset:44288
	v_add_f32_dpp v79, v78, v78 quad_perm:[3,2,1,0] row_mask:0xf bank_mask:0xf bound_ctrl:1
	ds_read_b32 v37, v12 offset:44288
	ds_read_b64 v[38:39], v13 offset:45264
	v_add_f32_dpp v80, v79, v79 row_half_mirror row_mask:0xf bank_mask:0xf bound_ctrl:1
	s_waitcnt lgkmcnt(10)
	v_pk_mul_f32 v[68:69], v[60:61], v[52:53] op_sel_hi:[1,0]
	v_add_f32_dpp v76, v80, v80 row_mirror row_mask:0xf bank_mask:0xf bound_ctrl:1
	v_pk_mul_f32 v[70:71], v[60:61], v[52:53] op_sel:[0,1] op_sel_hi:[1,1]
	v_pk_mul_f32 v[72:73], v[60:61], v[54:55] op_sel_hi:[1,0]
	v_mov_b32_dpp v77, v76 quad_perm:[1,0,3,2] row_mask:0xf bank_mask:0xf bound_ctrl:1
	v_pk_mul_f32 v[74:75], v[60:61], v[54:55] op_sel:[0,1] op_sel_hi:[1,1]
	v_pk_fma_f32 v[68:69], v[2:3], v[48:49], v[68:69] op_sel_hi:[1,0,1]
	v_pk_fma_f32 v[70:71], v[4:5], v[48:49], v[70:71] op_sel:[0,1,0] op_sel_hi:[1,1,1]
	v_pk_fma_f32 v[72:73], v[6:7], v[50:51], v[72:73] op_sel_hi:[1,0,1]
	v_pk_fma_f32 v[74:75], v[8:9], v[50:51], v[74:75] op_sel:[0,1,0] op_sel_hi:[1,1,1]
	v_pk_fma_f32 v[2:3], v[56:57], v[76:77], v[68:69] op_sel_hi:[0,1,1] neg_lo:[1,0,0] neg_hi:[1,0,0]
	v_pk_fma_f32 v[4:5], v[56:57], v[76:77], v[70:71] op_sel:[1,0,0] op_sel_hi:[1,1,1] neg_lo:[1,0,0] neg_hi:[1,0,0]
	s_waitcnt lgkmcnt(9)
; #define LAS __attribute__((address_space(3)))
; template <int CTRL> __device__ __forceinline__ float dppf(float x) { return __builtin_bit_cast(float, __builtin_amdgcn_mov_dpp(__builtin_bit_cast(int, x), CTRL, 0xf, 0xf, true)); }
; __device__ __forceinline__ float sum16(float x) { x = sum8(x); x += dppf<0x140>(x); return x; }
; __device__ __forceinline__ void rwkv_item(LAS unsigned char* lds, int l, const bf16_t* PROJ, const bf16_t* LO, bf16_t* YR, float* BON, int b, int h, int qv) {
;     ...
;             for (int t = 0; t < CH; ++t) {
;                 const int tn = (t + 1) & (CH - 1);
;                 const LAS float* pn = pk + tn * 64;
;                 const f32x4 nkk = *(const LAS f32x4*)(pn), nwr = *(const LAS f32x4*)(pn + 2048), nw = *(const LAS f32x4*)(pn + 4096), nk = *(const LAS f32x4*)(pn + 6144), na = *(const LAS f32x4*)(pn + 8192);
;                 const float nv0 = pv[tn * 32], nv1 = pv[tn * 32 + 4]; const f32x2 nsc = *(const LAS f32x2*)(ps + 2 * tn);
;                 float sa[2], yp[2];
; #pragma unroll
;                 for (int c = 0; c < 2; ++c) { const f32x2 pa = S23[c] * kk4.hi + S01[c] * kk4.lo, pb = S23[c] * wr4.hi + S01[c] * wr4.lo; sa[c] = pa.x + pa.y; yp[c] = pb.x + pb.y; }
; #pragma unroll
;                 for (int c = 0; c < 2; ++c) { sa[c] = sum16(sa[c]); yp[c] += dppf<0xB1>(yp[c]); yp[c] += dppf<0x4E>(yp[c]); }
; #pragma unroll
;                 for (int c = 0; c < 2; ++c) {
;                     S01[c] = S01[c] * w4.lo + (k4.lo * vv[c] - a4.lo * sa[c]);
;                     S23[c] = S23[c] * w4.hi + (k4.hi * vv[c] - a4.hi * sa[c]);
;                     py[(t * 32 + 4 * c) * 4] = yp[c] + 0.25f * (vv[c] * sc.x - sa[c] * sc.y);
;                 }
;                 kk4 = nkk; wr4 = nwr; w4 = nw; k4 = nk; a4 = na; vv[0] = nv0; vv[1] = nv1; sc = nsc;
;             }
	v_mul_f32_e32 v83, v60, v62
	v_add_f32_dpp v81, v67, v66 quad_perm:[1,0,3,2] row_mask:0xf bank_mask:0xf bound_ctrl:1
	v_pk_fma_f32 v[6:7], v[58:59], v[76:77], v[72:73] op_sel_hi:[0,1,1] neg_lo:[1,0,0] neg_hi:[1,0,0]
	v_pk_fma_f32 v[8:9], v[58:59], v[76:77], v[74:75] op_sel:[1,0,0] op_sel_hi:[1,1,1] neg_lo:[1,0,0] neg_hi:[1,0,0]
	v_add_f32_dpp v82, v81, v81 quad_perm:[3,2,1,0] row_mask:0xf bank_mask:0xf bound_ctrl:1
	v_fma_f32 v83, -v76, v63, v83
	v_fmac_f32_e32 v82, 0x3e800000, v83
	ds_write_b32 v14, v82 offset:12800
	s_waitcnt lgkmcnt(7)
	v_pk_mul_f32 v[64:65], v[2:3], v[16:17] op_sel_hi:[1,0]
	v_pk_mul_f32 v[66:67], v[2:3], v[20:21] op_sel_hi:[1,0]
	ds_read_b128 v[40:43], v10 offset:6912
	v_pk_fma_f32 v[64:65], v[4:5], v[16:17], v[64:65] op_sel:[0,1,0] op_sel_hi:[1,1,1]
	v_pk_fma_f32 v[66:67], v[4:5], v[20:21], v[66:67] op_sel:[0,1,0] op_sel_hi:[1,1,1]
	ds_read_b128 v[44:47], v10 offset:15104
	v_pk_fma_f32 v[64:65], v[6:7], v[18:19], v[64:65] op_sel_hi:[1,0,1]
	v_pk_fma_f32 v[66:67], v[6:7], v[22:23], v[66:67] op_sel_hi:[1,0,1]
	ds_read_b128 v[48:51], v10 offset:23296
	v_pk_fma_f32 v[64:65], v[8:9], v[18:19], v[64:65] op_sel:[0,1,0] op_sel_hi:[1,1,1]
	v_pk_fma_f32 v[66:67], v[8:9], v[22:23], v[66:67] op_sel:[0,1,0] op_sel_hi:[1,1,1]
	ds_read_b128 v[52:55], v10 offset:31488
	v_add_f32_dpp v78, v65, v64 quad_perm:[1,0,3,2] row_mask:0xf bank_mask:0xf bound_ctrl:1
	ds_read_b128 v[56:59], v10 offset:39680
	ds_read_b32 v60, v11 offset:44416
	v_add_f32_dpp v79, v78, v78 quad_perm:[3,2,1,0] row_mask:0xf bank_mask:0xf bound_ctrl:1
	ds_read_b32 v61, v12 offset:44416
	ds_read_b64 v[62:63], v13 offset:45272
	v_add_f32_dpp v80, v79, v79 row_half_mirror row_mask:0xf bank_mask:0xf bound_ctrl:1
	s_waitcnt lgkmcnt(10)
	v_pk_mul_f32 v[68:69], v[36:37], v[28:29] op_sel_hi:[1,0]
	v_add_f32_dpp v76, v80, v80 row_mirror row_mask:0xf bank_mask:0xf bound_ctrl:1
	v_pk_mul_f32 v[70:71], v[36:37], v[28:29] op_sel:[0,1] op_sel_hi:[1,1]
	v_pk_mul_f32 v[72:73], v[36:37], v[30:31] op_sel_hi:[1,0]
	v_mov_b32_dpp v77, v76 quad_perm:[1,0,3,2] row_mask:0xf bank_mask:0xf bound_ctrl:1
	v_pk_mul_f32 v[74:75], v[36:37], v[30:31] op_sel:[0,1] op_sel_hi:[1,1]
	v_pk_fma_f32 v[68:69], v[2:3], v[24:25], v[68:69] op_sel_hi:[1,0,1]
	v_pk_fma_f32 v[70:71], v[4:5], v[24:25], v[70:71] op_sel:[0,1,0] op_sel_hi:[1,1,1]
	v_pk_fma_f32 v[72:73], v[6:7], v[26:27], v[72:73] op_sel_hi:[1,0,1]
	v_pk_fma_f32 v[74:75], v[8:9], v[26:27], v[74:75] op_sel:[0,1,0] op_sel_hi:[1,1,1]
	v_pk_fma_f32 v[2:3], v[32:33], v[76:77], v[68:69] op_sel_hi:[0,1,1] neg_lo:[1,0,0] neg_hi:[1,0,0]
	v_pk_fma_f32 v[4:5], v[32:33], v[76:77], v[70:71] op_sel:[1,0,0] op_sel_hi:[1,1,1] neg_lo:[1,0,0] neg_hi:[1,0,0]
	s_waitcnt lgkmcnt(9)
	v_mul_f32_e32 v83, v36, v38
	v_add_f32_dpp v81, v67, v66 quad_perm:[1,0,3,2] row_mask:0xf bank_mask:0xf bound_ctrl:1
	v_pk_fma_f32 v[6:7], v[34:35], v[76:77], v[72:73] op_sel_hi:[0,1,1] neg_lo:[1,0,0] neg_hi:[1,0,0]
	v_pk_fma_f32 v[8:9], v[34:35], v[76:77], v[74:75] op_sel:[1,0,0] op_sel_hi:[1,1,1] neg_lo:[1,0,0] neg_hi:[1,0,0]
	v_add_f32_dpp v82, v81, v81 quad_perm:[3,2,1,0] row_mask:0xf bank_mask:0xf bound_ctrl:1
	v_fma_f32 v83, -v76, v39, v83
	v_fmac_f32_e32 v82, 0x3e800000, v83
	ds_write_b32 v14, v82 offset:13312
	s_waitcnt lgkmcnt(7)
	v_pk_mul_f32 v[64:65], v[2:3], v[40:41] op_sel_hi:[1,0]
	v_pk_mul_f32 v[66:67], v[2:3], v[44:45] op_sel_hi:[1,0]
	ds_read_b128 v[16:19], v10 offset:7168
	v_pk_fma_f32 v[64:65], v[4:5], v[40:41], v[64:65] op_sel:[0,1,0] op_sel_hi:[1,1,1]
	v_pk_fma_f32 v[66:67], v[4:5], v[44:45], v[66:67] op_sel:[0,1,0] op_sel_hi:[1,1,1]
	ds_read_b128 v[20:23], v10 offset:15360
	v_pk_fma_f32 v[64:65], v[6:7], v[42:43], v[64:65] op_sel_hi:[1,0,1]
	v_pk_fma_f32 v[66:67], v[6:7], v[46:47], v[66:67] op_sel_hi:[1,0,1]
	ds_read_b128 v[24:27], v10 offset:23552
	v_pk_fma_f32 v[64:65], v[8:9], v[42:43], v[64:65] op_sel:[0,1,0] op_sel_hi:[1,1,1]
	v_pk_fma_f32 v[66:67], v[8:9], v[46:47], v[66:67] op_sel:[0,1,0] op_sel_hi:[1,1,1]
	ds_read_b128 v[28:31], v10 offset:31744
	v_add_f32_dpp v78, v65, v64 quad_perm:[1,0,3,2] row_mask:0xf bank_mask:0xf bound_ctrl:1
	ds_read_b128 v[32:35], v10 offset:39936
	ds_read_b32 v36, v11 offset:44544
	v_add_f32_dpp v79, v78, v78 quad_perm:[3,2,1,0] row_mask:0xf bank_mask:0xf bound_ctrl:1
	ds_read_b32 v37, v12 offset:44544
	ds_read_b64 v[38:39], v13 offset:45280
	v_add_f32_dpp v80, v79, v79 row_half_mirror row_mask:0xf bank_mask:0xf bound_ctrl:1
	s_waitcnt lgkmcnt(10)
	v_pk_mul_f32 v[68:69], v[60:61], v[52:53] op_sel_hi:[1,0]
	v_add_f32_dpp v76, v80, v80 row_mirror row_mask:0xf bank_mask:0xf bound_ctrl:1
	v_pk_mul_f32 v[70:71], v[60:61], v[52:53] op_sel:[0,1] op_sel_hi:[1,1]
	v_pk_mul_f32 v[72:73], v[60:61], v[54:55] op_sel_hi:[1,0]
	v_mov_b32_dpp v77, v76 quad_perm:[1,0,3,2] row_mask:0xf bank_mask:0xf bound_ctrl:1
	v_pk_mul_f32 v[74:75], v[60:61], v[54:55] op_sel:[0,1] op_sel_hi:[1,1]
	v_pk_fma_f32 v[68:69], v[2:3], v[48:49], v[68:69] op_sel_hi:[1,0,1]
	v_pk_fma_f32 v[70:71], v[4:5], v[48:49], v[70:71] op_sel:[0,1,0] op_sel_hi:[1,1,1]
	v_pk_fma_f32 v[72:73], v[6:7], v[50:51], v[72:73] op_sel_hi:[1,0,1]
	v_pk_fma_f32 v[74:75], v[8:9], v[50:51], v[74:75] op_sel:[0,1,0] op_sel_hi:[1,1,1]
	v_pk_fma_f32 v[2:3], v[56:57], v[76:77], v[68:69] op_sel_hi:[0,1,1] neg_lo:[1,0,0] neg_hi:[1,0,0]
	v_pk_fma_f32 v[4:5], v[56:57], v[76:77], v[70:71] op_sel:[1,0,0] op_sel_hi:[1,1,1] neg_lo:[1,0,0] neg_hi:[1,0,0]
	s_waitcnt lgkmcnt(9)
; #define LAS __attribute__((address_space(3)))
; template <int CTRL> __device__ __forceinline__ float dppf(float x) { return __builtin_bit_cast(float, __builtin_amdgcn_mov_dpp(__builtin_bit_cast(int, x), CTRL, 0xf, 0xf, true)); }
; __device__ __forceinline__ float sum16(float x) { x = sum8(x); x += dppf<0x140>(x); return x; }
; __device__ __forceinline__ void rwkv_item(LAS unsigned char* lds, int l, const bf16_t* PROJ, const bf16_t* LO, bf16_t* YR, float* BON, int b, int h, int qv) {
;     ...
;             for (int t = 0; t < CH; ++t) {
;                 const int tn = (t + 1) & (CH - 1);
;                 const LAS float* pn = pk + tn * 64;
;                 const f32x4 nkk = *(const LAS f32x4*)(pn), nwr = *(const LAS f32x4*)(pn + 2048), nw = *(const LAS f32x4*)(pn + 4096), nk = *(const LAS f32x4*)(pn + 6144), na = *(const LAS f32x4*)(pn + 8192);
;                 const float nv0 = pv[tn * 32], nv1 = pv[tn * 32 + 4]; const f32x2 nsc = *(const LAS f32x2*)(ps + 2 * tn);
;                 float sa[2], yp[2];
; #pragma unroll
;                 for (int c = 0; c < 2; ++c) { const f32x2 pa = S23[c] * kk4.hi + S01[c] * kk4.lo, pb = S23[c] * wr4.hi + S01[c] * wr4.lo; sa[c] = pa.x + pa.y; yp[c] = pb.x + pb.y; }
; #pragma unroll
;                 for (int c = 0; c < 2; ++c) { sa[c] = sum16(sa[c]); yp[c] += dppf<0xB1>(yp[c]); yp[c] += dppf<0x4E>(yp[c]); }
; #pragma unroll
;                 for (int c = 0; c < 2; ++c) {
;                     S01[c] = S01[c] * w4.lo + (k4.lo * vv[c] - a4.lo * sa[c]);
;                     S23[c] = S23[c] * w4.hi + (k4.hi * vv[c] - a4.hi * sa[c]);
;                     py[(t * 32 + 4 * c) * 4] = yp[c] + 0.25f * (vv[c] * sc.x - sa[c] * sc.y);
;                 }
;                 kk4 = nkk; wr4 = nwr; w4 = nw; k4 = nk; a4 = na; vv[0] = nv0; vv[1] = nv1; sc = nsc;
;             }
	v_mul_f32_e32 v83, v60, v62
	v_add_f32_dpp v81, v67, v66 quad_perm:[1,0,3,2] row_mask:0xf bank_mask:0xf bound_ctrl:1
	v_pk_fma_f32 v[6:7], v[58:59], v[76:77], v[72:73] op_sel_hi:[0,1,1] neg_lo:[1,0,0] neg_hi:[1,0,0]
	v_pk_fma_f32 v[8:9], v[58:59], v[76:77], v[74:75] op_sel:[1,0,0] op_sel_hi:[1,1,1] neg_lo:[1,0,0] neg_hi:[1,0,0]
	v_add_f32_dpp v82, v81, v81 quad_perm:[3,2,1,0] row_mask:0xf bank_mask:0xf bound_ctrl:1
	v_fma_f32 v83, -v76, v63, v83
	v_fmac_f32_e32 v82, 0x3e800000, v83
	ds_write_b32 v14, v82 offset:13824
	s_waitcnt lgkmcnt(7)
	v_pk_mul_f32 v[64:65], v[2:3], v[16:17] op_sel_hi:[1,0]
	v_pk_mul_f32 v[66:67], v[2:3], v[20:21] op_sel_hi:[1,0]
	ds_read_b128 v[40:43], v10 offset:7424
	v_pk_fma_f32 v[64:65], v[4:5], v[16:17], v[64:65] op_sel:[0,1,0] op_sel_hi:[1,1,1]
	v_pk_fma_f32 v[66:67], v[4:5], v[20:21], v[66:67] op_sel:[0,1,0] op_sel_hi:[1,1,1]
	ds_read_b128 v[44:47], v10 offset:15616
	v_pk_fma_f32 v[64:65], v[6:7], v[18:19], v[64:65] op_sel_hi:[1,0,1]
	v_pk_fma_f32 v[66:67], v[6:7], v[22:23], v[66:67] op_sel_hi:[1,0,1]
	ds_read_b128 v[48:51], v10 offset:23808
	v_pk_fma_f32 v[64:65], v[8:9], v[18:19], v[64:65] op_sel:[0,1,0] op_sel_hi:[1,1,1]
	v_pk_fma_f32 v[66:67], v[8:9], v[22:23], v[66:67] op_sel:[0,1,0] op_sel_hi:[1,1,1]
	ds_read_b128 v[52:55], v10 offset:32000
	v_add_f32_dpp v78, v65, v64 quad_perm:[1,0,3,2] row_mask:0xf bank_mask:0xf bound_ctrl:1
	ds_read_b128 v[56:59], v10 offset:40192
	ds_read_b32 v60, v11 offset:44672
	v_add_f32_dpp v79, v78, v78 quad_perm:[3,2,1,0] row_mask:0xf bank_mask:0xf bound_ctrl:1
	ds_read_b32 v61, v12 offset:44672
	ds_read_b64 v[62:63], v13 offset:45288
	v_add_f32_dpp v80, v79, v79 row_half_mirror row_mask:0xf bank_mask:0xf bound_ctrl:1
	s_waitcnt lgkmcnt(10)
	v_pk_mul_f32 v[68:69], v[36:37], v[28:29] op_sel_hi:[1,0]
	v_add_f32_dpp v76, v80, v80 row_mirror row_mask:0xf bank_mask:0xf bound_ctrl:1
	v_pk_mul_f32 v[70:71], v[36:37], v[28:29] op_sel:[0,1] op_sel_hi:[1,1]
	v_pk_mul_f32 v[72:73], v[36:37], v[30:31] op_sel_hi:[1,0]
	v_mov_b32_dpp v77, v76 quad_perm:[1,0,3,2] row_mask:0xf bank_mask:0xf bound_ctrl:1
	v_pk_mul_f32 v[74:75], v[36:37], v[30:31] op_sel:[0,1] op_sel_hi:[1,1]
	v_pk_fma_f32 v[68:69], v[2:3], v[24:25], v[68:69] op_sel_hi:[1,0,1]
	v_pk_fma_f32 v[70:71], v[4:5], v[24:25], v[70:71] op_sel:[0,1,0] op_sel_hi:[1,1,1]
	v_pk_fma_f32 v[72:73], v[6:7], v[26:27], v[72:73] op_sel_hi:[1,0,1]
	v_pk_fma_f32 v[74:75], v[8:9], v[26:27], v[74:75] op_sel:[0,1,0] op_sel_hi:[1,1,1]
	v_pk_fma_f32 v[2:3], v[32:33], v[76:77], v[68:69] op_sel_hi:[0,1,1] neg_lo:[1,0,0] neg_hi:[1,0,0]
	v_pk_fma_f32 v[4:5], v[32:33], v[76:77], v[70:71] op_sel:[1,0,0] op_sel_hi:[1,1,1] neg_lo:[1,0,0] neg_hi:[1,0,0]
	s_waitcnt lgkmcnt(9)
	v_mul_f32_e32 v83, v36, v38
	v_add_f32_dpp v81, v67, v66 quad_perm:[1,0,3,2] row_mask:0xf bank_mask:0xf bound_ctrl:1
	v_pk_fma_f32 v[6:7], v[34:35], v[76:77], v[72:73] op_sel_hi:[0,1,1] neg_lo:[1,0,0] neg_hi:[1,0,0]
	v_pk_fma_f32 v[8:9], v[34:35], v[76:77], v[74:75] op_sel:[1,0,0] op_sel_hi:[1,1,1] neg_lo:[1,0,0] neg_hi:[1,0,0]
	v_add_f32_dpp v82, v81, v81 quad_perm:[3,2,1,0] row_mask:0xf bank_mask:0xf bound_ctrl:1
	v_fma_f32 v83, -v76, v39, v83
	v_fmac_f32_e32 v82, 0x3e800000, v83
	ds_write_b32 v14, v82 offset:14336
	s_waitcnt lgkmcnt(7)
	v_pk_mul_f32 v[64:65], v[2:3], v[40:41] op_sel_hi:[1,0]
	v_pk_mul_f32 v[66:67], v[2:3], v[44:45] op_sel_hi:[1,0]
	ds_read_b128 v[16:19], v10 offset:7680
	v_pk_fma_f32 v[64:65], v[4:5], v[40:41], v[64:65] op_sel:[0,1,0] op_sel_hi:[1,1,1]
	v_pk_fma_f32 v[66:67], v[4:5], v[44:45], v[66:67] op_sel:[0,1,0] op_sel_hi:[1,1,1]
	ds_read_b128 v[20:23], v10 offset:15872
	v_pk_fma_f32 v[64:65], v[6:7], v[42:43], v[64:65] op_sel_hi:[1,0,1]
	v_pk_fma_f32 v[66:67], v[6:7], v[46:47], v[66:67] op_sel_hi:[1,0,1]
	ds_read_b128 v[24:27], v10 offset:24064
	v_pk_fma_f32 v[64:65], v[8:9], v[42:43], v[64:65] op_sel:[0,1,0] op_sel_hi:[1,1,1]
	v_pk_fma_f32 v[66:67], v[8:9], v[46:47], v[66:67] op_sel:[0,1,0] op_sel_hi:[1,1,1]
	ds_read_b128 v[28:31], v10 offset:32256
	v_add_f32_dpp v78, v65, v64 quad_perm:[1,0,3,2] row_mask:0xf bank_mask:0xf bound_ctrl:1
	ds_read_b128 v[32:35], v10 offset:40448
	ds_read_b32 v36, v11 offset:44800
	v_add_f32_dpp v79, v78, v78 quad_perm:[3,2,1,0] row_mask:0xf bank_mask:0xf bound_ctrl:1
	ds_read_b32 v37, v12 offset:44800
	ds_read_b64 v[38:39], v13 offset:45296
	v_add_f32_dpp v80, v79, v79 row_half_mirror row_mask:0xf bank_mask:0xf bound_ctrl:1
	s_waitcnt lgkmcnt(10)
	v_pk_mul_f32 v[68:69], v[60:61], v[52:53] op_sel_hi:[1,0]
	v_add_f32_dpp v76, v80, v80 row_mirror row_mask:0xf bank_mask:0xf bound_ctrl:1
	v_pk_mul_f32 v[70:71], v[60:61], v[52:53] op_sel:[0,1] op_sel_hi:[1,1]
	v_pk_mul_f32 v[72:73], v[60:61], v[54:55] op_sel_hi:[1,0]
	v_mov_b32_dpp v77, v76 quad_perm:[1,0,3,2] row_mask:0xf bank_mask:0xf bound_ctrl:1
	v_pk_mul_f32 v[74:75], v[60:61], v[54:55] op_sel:[0,1] op_sel_hi:[1,1]
	v_pk_fma_f32 v[68:69], v[2:3], v[48:49], v[68:69] op_sel_hi:[1,0,1]
	v_pk_fma_f32 v[70:71], v[4:5], v[48:49], v[70:71] op_sel:[0,1,0] op_sel_hi:[1,1,1]
	v_pk_fma_f32 v[72:73], v[6:7], v[50:51], v[72:73] op_sel_hi:[1,0,1]
	v_pk_fma_f32 v[74:75], v[8:9], v[50:51], v[74:75] op_sel:[0,1,0] op_sel_hi:[1,1,1]
	v_pk_fma_f32 v[2:3], v[56:57], v[76:77], v[68:69] op_sel_hi:[0,1,1] neg_lo:[1,0,0] neg_hi:[1,0,0]
	v_pk_fma_f32 v[4:5], v[56:57], v[76:77], v[70:71] op_sel:[1,0,0] op_sel_hi:[1,1,1] neg_lo:[1,0,0] neg_hi:[1,0,0]
	s_waitcnt lgkmcnt(9)
; #define LAS __attribute__((address_space(3)))
; template <int CTRL> __device__ __forceinline__ float dppf(float x) { return __builtin_bit_cast(float, __builtin_amdgcn_mov_dpp(__builtin_bit_cast(int, x), CTRL, 0xf, 0xf, true)); }
; __device__ __forceinline__ float sum16(float x) { x = sum8(x); x += dppf<0x140>(x); return x; }
; __device__ __forceinline__ void rwkv_item(LAS unsigned char* lds, int l, const bf16_t* PROJ, const bf16_t* LO, bf16_t* YR, float* BON, int b, int h, int qv) {
;     ...
;             for (int t = 0; t < CH; ++t) {
;                 const int tn = (t + 1) & (CH - 1);
;                 const LAS float* pn = pk + tn * 64;
;                 const f32x4 nkk = *(const LAS f32x4*)(pn), nwr = *(const LAS f32x4*)(pn + 2048), nw = *(const LAS f32x4*)(pn + 4096), nk = *(const LAS f32x4*)(pn + 6144), na = *(const LAS f32x4*)(pn + 8192);
;                 const float nv0 = pv[tn * 32], nv1 = pv[tn * 32 + 4]; const f32x2 nsc = *(const LAS f32x2*)(ps + 2 * tn);
;                 float sa[2], yp[2];
; #pragma unroll
;                 for (int c = 0; c < 2; ++c) { const f32x2 pa = S23[c] * kk4.hi + S01[c] * kk4.lo, pb = S23[c] * wr4.hi + S01[c] * wr4.lo; sa[c] = pa.x + pa.y; yp[c] = pb.x + pb.y; }
; #pragma unroll
;                 for (int c = 0; c < 2; ++c) { sa[c] = sum16(sa[c]); yp[c] += dppf<0xB1>(yp[c]); yp[c] += dppf<0x4E>(yp[c]); }
; #pragma unroll
;                 for (int c = 0; c < 2; ++c) {
;                     S01[c] = S01[c] * w4.lo + (k4.lo * vv[c] - a4.lo * sa[c]);
;                     S23[c] = S23[c] * w4.hi + (k4.hi * vv[c] - a4.hi * sa[c]);
;                     py[(t * 32 + 4 * c) * 4] = yp[c] + 0.25f * (vv[c] * sc.x - sa[c] * sc.y);
;                 }
;                 kk4 = nkk; wr4 = nwr; w4 = nw; k4 = nk; a4 = na; vv[0] = nv0; vv[1] = nv1; sc = nsc;
;             }
;             __syncthreads();
;         }
	v_mul_f32_e32 v83, v60, v62
	v_add_f32_dpp v81, v67, v66 quad_perm:[1,0,3,2] row_mask:0xf bank_mask:0xf bound_ctrl:1
	v_pk_fma_f32 v[6:7], v[58:59], v[76:77], v[72:73] op_sel_hi:[0,1,1] neg_lo:[1,0,0] neg_hi:[1,0,0]
	v_pk_fma_f32 v[8:9], v[58:59], v[76:77], v[74:75] op_sel:[1,0,0] op_sel_hi:[1,1,1] neg_lo:[1,0,0] neg_hi:[1,0,0]
	v_add_f32_dpp v82, v81, v81 quad_perm:[3,2,1,0] row_mask:0xf bank_mask:0xf bound_ctrl:1
	v_fma_f32 v83, -v76, v63, v83
	v_fmac_f32_e32 v82, 0x3e800000, v83
	ds_write_b32 v14, v82 offset:14848
	s_waitcnt lgkmcnt(7)
	v_pk_mul_f32 v[64:65], v[2:3], v[16:17] op_sel_hi:[1,0]
	v_pk_mul_f32 v[66:67], v[2:3], v[20:21] op_sel_hi:[1,0]
	ds_read_b128 v[40:43], v10 offset:7936
	v_pk_fma_f32 v[64:65], v[4:5], v[16:17], v[64:65] op_sel:[0,1,0] op_sel_hi:[1,1,1]
	v_pk_fma_f32 v[66:67], v[4:5], v[20:21], v[66:67] op_sel:[0,1,0] op_sel_hi:[1,1,1]
	ds_read_b128 v[44:47], v10 offset:16128
	v_pk_fma_f32 v[64:65], v[6:7], v[18:19], v[64:65] op_sel_hi:[1,0,1]
	v_pk_fma_f32 v[66:67], v[6:7], v[22:23], v[66:67] op_sel_hi:[1,0,1]
	ds_read_b128 v[48:51], v10 offset:24320
	v_pk_fma_f32 v[64:65], v[8:9], v[18:19], v[64:65] op_sel:[0,1,0] op_sel_hi:[1,1,1]
	v_pk_fma_f32 v[66:67], v[8:9], v[22:23], v[66:67] op_sel:[0,1,0] op_sel_hi:[1,1,1]
	ds_read_b128 v[52:55], v10 offset:32512
	v_add_f32_dpp v78, v65, v64 quad_perm:[1,0,3,2] row_mask:0xf bank_mask:0xf bound_ctrl:1
	ds_read_b128 v[56:59], v10 offset:40704
	ds_read_b32 v60, v11 offset:44928
	v_add_f32_dpp v79, v78, v78 quad_perm:[3,2,1,0] row_mask:0xf bank_mask:0xf bound_ctrl:1
	ds_read_b32 v61, v12 offset:44928
	ds_read_b64 v[62:63], v13 offset:45304
	v_add_f32_dpp v80, v79, v79 row_half_mirror row_mask:0xf bank_mask:0xf bound_ctrl:1
	s_waitcnt lgkmcnt(10)
	v_pk_mul_f32 v[68:69], v[36:37], v[28:29] op_sel_hi:[1,0]
	v_add_f32_dpp v76, v80, v80 row_mirror row_mask:0xf bank_mask:0xf bound_ctrl:1
	v_pk_mul_f32 v[70:71], v[36:37], v[28:29] op_sel:[0,1] op_sel_hi:[1,1]
	v_pk_mul_f32 v[72:73], v[36:37], v[30:31] op_sel_hi:[1,0]
	v_mov_b32_dpp v77, v76 quad_perm:[1,0,3,2] row_mask:0xf bank_mask:0xf bound_ctrl:1
	v_pk_mul_f32 v[74:75], v[36:37], v[30:31] op_sel:[0,1] op_sel_hi:[1,1]
	v_pk_fma_f32 v[68:69], v[2:3], v[24:25], v[68:69] op_sel_hi:[1,0,1]
	v_pk_fma_f32 v[70:71], v[4:5], v[24:25], v[70:71] op_sel:[0,1,0] op_sel_hi:[1,1,1]
	v_pk_fma_f32 v[72:73], v[6:7], v[26:27], v[72:73] op_sel_hi:[1,0,1]
	v_pk_fma_f32 v[74:75], v[8:9], v[26:27], v[74:75] op_sel:[0,1,0] op_sel_hi:[1,1,1]
	v_pk_fma_f32 v[2:3], v[32:33], v[76:77], v[68:69] op_sel_hi:[0,1,1] neg_lo:[1,0,0] neg_hi:[1,0,0]
	v_pk_fma_f32 v[4:5], v[32:33], v[76:77], v[70:71] op_sel:[1,0,0] op_sel_hi:[1,1,1] neg_lo:[1,0,0] neg_hi:[1,0,0]
	s_waitcnt lgkmcnt(9)
	v_mul_f32_e32 v83, v36, v38
	v_add_f32_dpp v81, v67, v66 quad_perm:[1,0,3,2] row_mask:0xf bank_mask:0xf bound_ctrl:1
	v_pk_fma_f32 v[6:7], v[34:35], v[76:77], v[72:73] op_sel_hi:[0,1,1] neg_lo:[1,0,0] neg_hi:[1,0,0]
	v_pk_fma_f32 v[8:9], v[34:35], v[76:77], v[74:75] op_sel:[1,0,0] op_sel_hi:[1,1,1] neg_lo:[1,0,0] neg_hi:[1,0,0]
	v_add_f32_dpp v82, v81, v81 quad_perm:[3,2,1,0] row_mask:0xf bank_mask:0xf bound_ctrl:1
	v_fma_f32 v83, -v76, v39, v83
	v_fmac_f32_e32 v82, 0x3e800000, v83
	ds_write_b32 v14, v82 offset:15360
	s_waitcnt lgkmcnt(7)
	v_pk_mul_f32 v[64:65], v[2:3], v[40:41] op_sel_hi:[1,0]
	v_pk_mul_f32 v[66:67], v[2:3], v[44:45] op_sel_hi:[1,0]
	s_nop 0
	v_pk_fma_f32 v[64:65], v[4:5], v[40:41], v[64:65] op_sel:[0,1,0] op_sel_hi:[1,1,1]
	v_pk_fma_f32 v[66:67], v[4:5], v[44:45], v[66:67] op_sel:[0,1,0] op_sel_hi:[1,1,1]
	s_nop 0
	v_pk_fma_f32 v[64:65], v[6:7], v[42:43], v[64:65] op_sel_hi:[1,0,1]
	v_pk_fma_f32 v[66:67], v[6:7], v[46:47], v[66:67] op_sel_hi:[1,0,1]
	s_nop 0
	v_pk_fma_f32 v[64:65], v[8:9], v[42:43], v[64:65] op_sel:[0,1,0] op_sel_hi:[1,1,1]
	v_pk_fma_f32 v[66:67], v[8:9], v[46:47], v[66:67] op_sel:[0,1,0] op_sel_hi:[1,1,1]
	s_nop 0
	v_add_f32_dpp v78, v65, v64 quad_perm:[1,0,3,2] row_mask:0xf bank_mask:0xf bound_ctrl:1
	s_nop 0
	s_nop 0
	v_add_f32_dpp v79, v78, v78 quad_perm:[3,2,1,0] row_mask:0xf bank_mask:0xf bound_ctrl:1
	s_nop 0
	s_nop 0
	v_add_f32_dpp v80, v79, v79 row_half_mirror row_mask:0xf bank_mask:0xf bound_ctrl:1
	s_waitcnt lgkmcnt(2)
	v_pk_mul_f32 v[68:69], v[60:61], v[52:53] op_sel_hi:[1,0]
	v_add_f32_dpp v76, v80, v80 row_mirror row_mask:0xf bank_mask:0xf bound_ctrl:1
	v_pk_mul_f32 v[70:71], v[60:61], v[52:53] op_sel:[0,1] op_sel_hi:[1,1]
	v_pk_mul_f32 v[72:73], v[60:61], v[54:55] op_sel_hi:[1,0]
	v_mov_b32_dpp v77, v76 quad_perm:[1,0,3,2] row_mask:0xf bank_mask:0xf bound_ctrl:1
	v_pk_mul_f32 v[74:75], v[60:61], v[54:55] op_sel:[0,1] op_sel_hi:[1,1]
	v_pk_fma_f32 v[68:69], v[2:3], v[48:49], v[68:69] op_sel_hi:[1,0,1]
	v_pk_fma_f32 v[70:71], v[4:5], v[48:49], v[70:71] op_sel:[0,1,0] op_sel_hi:[1,1,1]
	v_pk_fma_f32 v[72:73], v[6:7], v[50:51], v[72:73] op_sel_hi:[1,0,1]
	v_pk_fma_f32 v[74:75], v[8:9], v[50:51], v[74:75] op_sel:[0,1,0] op_sel_hi:[1,1,1]
	v_pk_fma_f32 v[2:3], v[56:57], v[76:77], v[68:69] op_sel_hi:[0,1,1] neg_lo:[1,0,0] neg_hi:[1,0,0]
	v_pk_fma_f32 v[4:5], v[56:57], v[76:77], v[70:71] op_sel:[1,0,0] op_sel_hi:[1,1,1] neg_lo:[1,0,0] neg_hi:[1,0,0]
	s_waitcnt lgkmcnt(1)
	v_mul_f32_e32 v83, v60, v62
	v_add_f32_dpp v81, v67, v66 quad_perm:[1,0,3,2] row_mask:0xf bank_mask:0xf bound_ctrl:1
	v_pk_fma_f32 v[6:7], v[58:59], v[76:77], v[72:73] op_sel_hi:[0,1,1] neg_lo:[1,0,0] neg_hi:[1,0,0]
	v_pk_fma_f32 v[8:9], v[58:59], v[76:77], v[74:75] op_sel:[1,0,0] op_sel_hi:[1,1,1] neg_lo:[1,0,0] neg_hi:[1,0,0]
	v_add_f32_dpp v82, v81, v81 quad_perm:[3,2,1,0] row_mask:0xf bank_mask:0xf bound_ctrl:1
	v_fma_f32 v83, -v76, v63, v83
	v_fmac_f32_e32 v82, 0x3e800000, v83
	ds_write_b32 v14, v82 offset:15872
	s_add_i32 s30, s30, 1
	s_cmpk_eq_i32 s30, 0x80
	s_waitcnt lgkmcnt(0)
	s_barrier
	s_cbranch_scc0 .Lscan_chunk
	s_setprio 0
	s_mov_b64 s[30:31], 0
